# EpiRes epilogues: residual loads coalesced by lane transpose + ds_bpermute back; ssq cross-row shuffles via v_permlane16/32_swap instead of ds_bpermute
# speedup vs baseline: 1.0393x; 1.0095x over previous
;     __device__ __forceinline__ void operator()(const f32x4 (&acc)[2][2][4][2], const Unit& u, int wr, int wc, int fr, int fq) const {
;     ...
;             u32x4 hv[2][4][2];
; #pragma unroll
;             for (int ai = 0; ai < 2; ++ai)
; #pragma unroll
;                 for (int m = 0; m < 4; ++m)
; #pragma unroll
;                     for (int bj = 0; bj < 2; ++bj) hv[ai][m][bj] = *(const u32x4*)(hb + (size_t)(u.pm * BM + rl0 + ai * HALF + m * 16) * 1024 + col0 + bj * HALF);
;             asm volatile("" ::: "memory");
.LBB0_380:
	s_mov_b64 s[58:59], 0
	s_cbranch_execz .LBB0_378
	v_mbcnt_lo_u32_b32 v246, -1, 0
	v_mbcnt_hi_u32_b32 v246, -1, v246
	v_and_b32_e32 v249, 3, v246
	v_lshrrev_b32_e32 v245, 4, v246
	v_sub_u32_e32 v245, v249, v245
	v_lshlrev_b32_e32 v245, 4, v245
	v_and_b32_e32 v244, 15, v246
	v_lshrrev_b32_e32 v249, 2, v246
	v_sub_u32_e32 v249, v249, v244
	v_lshl_add_u32 v244, v244, 2, 0
	v_lshrrev_b32_e32 v246, 4, v246
	v_add_u32_e32 v246, v244, v246
	v_lshlrev_b32_e32 v246, 2, v246
	v_lshl_add_u32 v244, v249, 11, v245
	v_ashrrev_i32_e32 v245, 31, v244
	v_lshlrev_b64 v[210:211], 1, v[206:207]
	s_waitcnt lgkmcnt(0)
	v_lshl_add_u64 v[130:131], s[40:41], 0, v[210:211]
	v_lshlrev_b64 v[212:213], 11, v[208:209]
	v_lshl_add_u64 v[130:131], v[130:131], 0, v[212:213]
	v_lshl_add_u64 v[250:251], v[130:131], 0, v[244:245]
	global_load_dwordx4 v[218:221], v[250:251], off
	v_lshl_add_u64 v[250:251], v[130:131], 0, v[244:245]
	global_load_dwordx4 v[222:225], v[250:251], off offset:256
	v_add_co_u32_e32 v134, vcc, 0x8000, v130
	s_mov_b32 s53, 0x10000
	s_nop 0
	v_addc_co_u32_e32 v135, vcc, 0, v131, vcc
	s_mov_b64 s[58:59], 0x8000
	v_add_co_u32_e32 v144, vcc, s53, v130
	v_lshl_add_u64 v[132:133], v[130:131], 0, s[58:59]
	s_nop 0
	v_addc_co_u32_e32 v145, vcc, 0, v131, vcc
	s_mov_b32 s53, 0x18000
	v_lshl_add_u64 v[250:251], v[134:135], 0, v[244:245]
	global_load_dwordx4 v[182:185], v[250:251], off
	v_lshl_add_u64 v[250:251], v[132:133], 0, v[244:245]
	global_load_dwordx4 v[178:181], v[250:251], off offset:256
	v_add_co_u32_e32 v132, vcc, s53, v130
	s_mov_b32 s53, 0x40000
	s_nop 0
	v_addc_co_u32_e32 v133, vcc, 0, v131, vcc
	s_mov_b64 s[58:59], 0x10000
	v_add_co_u32_e32 v134, vcc, s53, v130
	v_lshl_add_u64 v[136:137], v[130:131], 0, s[58:59]
	s_mov_b64 s[58:59], 0x18000
	v_addc_co_u32_e32 v135, vcc, 0, v131, vcc
	s_mov_b32 s53, 0x48000
	v_lshl_add_u64 v[138:139], v[130:131], 0, s[58:59]
	s_mov_b64 s[58:59], 0x40000
	v_lshl_add_u64 v[250:251], v[144:145], 0, v[244:245]
	global_load_dwordx4 v[174:177], v[250:251], off
	v_lshl_add_u64 v[250:251], v[136:137], 0, v[244:245]
	global_load_dwordx4 v[170:173], v[250:251], off offset:256
	v_lshl_add_u64 v[250:251], v[132:133], 0, v[244:245]
	global_load_dwordx4 v[166:169], v[250:251], off
	v_lshl_add_u64 v[250:251], v[138:139], 0, v[244:245]
	global_load_dwordx4 v[162:165], v[250:251], off offset:256
	v_add_co_u32_e32 v132, vcc, s53, v130
	v_lshl_add_u64 v[140:141], v[130:131], 0, s[58:59]
	s_mov_b64 s[58:59], 0x48000
	v_addc_co_u32_e32 v133, vcc, 0, v131, vcc
	s_mov_b32 s53, 0x50000
	v_lshl_add_u64 v[142:143], v[130:131], 0, s[58:59]
	s_mov_b64 s[58:59], 0x50000
	v_lshl_add_u64 v[250:251], v[134:135], 0, v[244:245]
	global_load_dwordx4 v[158:161], v[250:251], off
	v_lshl_add_u64 v[250:251], v[140:141], 0, v[244:245]
	global_load_dwordx4 v[154:157], v[250:251], off offset:256
	v_add_co_u32_e32 v134, vcc, s53, v130
	v_lshl_add_u64 v[226:227], v[130:131], 0, s[58:59]
	s_mov_b64 s[58:59], 0x58000
	v_addc_co_u32_e32 v135, vcc, 0, v131, vcc
	s_mov_b32 s53, 0x58000
	v_lshl_add_u64 v[228:229], v[130:131], 0, s[58:59]
	v_add_co_u32_e32 v130, vcc, s53, v130
	v_lshl_add_u64 v[250:251], v[132:133], 0, v[244:245]
	global_load_dwordx4 v[150:153], v[250:251], off
	v_lshl_add_u64 v[250:251], v[142:143], 0, v[244:245]
	global_load_dwordx4 v[146:149], v[250:251], off offset:256
	v_addc_co_u32_e32 v131, vcc, 0, v131, vcc
	v_lshl_add_u64 v[250:251], v[134:135], 0, v[244:245]
	global_load_dwordx4 v[142:145], v[250:251], off
	v_lshl_add_u64 v[250:251], v[226:227], 0, v[244:245]
	global_load_dwordx4 v[138:141], v[250:251], off offset:256
	s_nop 0
	v_lshl_add_u64 v[250:251], v[130:131], 0, v[244:245]
	global_load_dwordx4 v[134:137], v[250:251], off
	s_nop 0
	v_lshl_add_u64 v[250:251], v[228:229], 0, v[244:245]
	global_load_dwordx4 v[130:133], v[250:251], off offset:256
	v_cmp_eq_u32_e64 s[58:59], 0, v217
	s_lshl_b32 s60, s80, 2
	s_ashr_i32 s61, s60, 31
	s_waitcnt vmcnt(0)
	ds_bpermute_b32 v218, v246, v218
	ds_bpermute_b32 v219, v246, v219
	ds_bpermute_b32 v220, v246, v220
	ds_bpermute_b32 v221, v246, v221
	ds_bpermute_b32 v222, v246, v222
	ds_bpermute_b32 v223, v246, v223
	ds_bpermute_b32 v224, v246, v224
	ds_bpermute_b32 v225, v246, v225
	ds_bpermute_b32 v182, v246, v182
	ds_bpermute_b32 v183, v246, v183
	ds_bpermute_b32 v184, v246, v184
	ds_bpermute_b32 v185, v246, v185
	ds_bpermute_b32 v178, v246, v178
	ds_bpermute_b32 v179, v246, v179
	ds_bpermute_b32 v180, v246, v180
	ds_bpermute_b32 v181, v246, v181
	ds_bpermute_b32 v174, v246, v174
	ds_bpermute_b32 v175, v246, v175
	ds_bpermute_b32 v176, v246, v176
	ds_bpermute_b32 v177, v246, v177
	ds_bpermute_b32 v170, v246, v170
	ds_bpermute_b32 v171, v246, v171
	ds_bpermute_b32 v172, v246, v172
	ds_bpermute_b32 v173, v246, v173
	ds_bpermute_b32 v166, v246, v166
	ds_bpermute_b32 v167, v246, v167
	ds_bpermute_b32 v168, v246, v168
	ds_bpermute_b32 v169, v246, v169
	ds_bpermute_b32 v162, v246, v162
	ds_bpermute_b32 v163, v246, v163
	ds_bpermute_b32 v164, v246, v164
	ds_bpermute_b32 v165, v246, v165
	ds_bpermute_b32 v158, v246, v158
	ds_bpermute_b32 v159, v246, v159
	ds_bpermute_b32 v160, v246, v160
	ds_bpermute_b32 v161, v246, v161
	ds_bpermute_b32 v154, v246, v154
	ds_bpermute_b32 v155, v246, v155
	ds_bpermute_b32 v156, v246, v156
	ds_bpermute_b32 v157, v246, v157
	ds_bpermute_b32 v150, v246, v150
	ds_bpermute_b32 v151, v246, v151
	ds_bpermute_b32 v152, v246, v152
	ds_bpermute_b32 v153, v246, v153
	ds_bpermute_b32 v146, v246, v146
	ds_bpermute_b32 v147, v246, v147
	ds_bpermute_b32 v148, v246, v148
	ds_bpermute_b32 v149, v246, v149
	ds_bpermute_b32 v142, v246, v142
	ds_bpermute_b32 v143, v246, v143
	ds_bpermute_b32 v144, v246, v144
	ds_bpermute_b32 v145, v246, v145
	ds_bpermute_b32 v138, v246, v138
	ds_bpermute_b32 v139, v246, v139
	ds_bpermute_b32 v140, v246, v140
	ds_bpermute_b32 v141, v246, v141
	ds_bpermute_b32 v134, v246, v134
	ds_bpermute_b32 v135, v246, v135
	ds_bpermute_b32 v136, v246, v136
	ds_bpermute_b32 v137, v246, v137
	ds_bpermute_b32 v130, v246, v130
	ds_bpermute_b32 v131, v246, v131
	ds_bpermute_b32 v132, v246, v132
	ds_bpermute_b32 v133, v246, v133
	s_waitcnt lgkmcnt(0)
; __device__ __forceinline__ unsigned cvt_pk_bf16(float lo, float hi) { unsigned r; asm volatile("v_cvt_pk_bf16_f32 %0, %1, %2" : "=v"(r) : "v"(lo), "v"(hi)); return r; }
;     __device__ __forceinline__ void finish_half(const f32x4 (&acc)[2][2][4][2], const f32x4 (&r)[4][2][2], const Unit& u, int ai, int rl0, int col0, int wc, int fq) const {
;     ...
;         for (int m = 0; m < 4; ++m) { const size_t row = (size_t)(u.pm * BM + rl0 + ai * HALF + m * 16); const size_t off = row * 1024 + col0; float q = 0.f;
; #pragma unroll
;             for (int bj = 0; bj < 2; ++bj) {
;                 const f32x4 v0 = acc[ai][bj][m][0] + r[m][bj][0], v1 = acc[ai][bj][m][1] + r[m][bj][1];
;                 if (out32) { *(f32x4*)(out32 + off + bj * HALF) = v0; *(f32x4*)(out32 + off + bj * HALF + 4) = v1; }
;                 q += (v0[0] * v0[0] + v0[1] * v0[1]) + (v0[2] * v0[2] + v0[3] * v0[3]) + (v1[0] * v1[0] + v1[1] * v1[1]) + (v1[2] * v1[2] + v1[3] * v1[3]);
;                 u32x4 w; w.x = cvt_pk_bf16(v0[0], v0[1]); w.y = cvt_pk_bf16(v0[2], v0[3]); w.z = cvt_pk_bf16(v1[0], v1[1]); w.w = cvt_pk_bf16(v1[2], v1[3]);
;                 *(u32x4*)(hb + off + bj * HALF) = w; }
;             q += __shfl_xor(q, 16); q += __shfl_xor(q, 32);
;             if (fq == 0) ssq[row * 16 + u.pn * 4 + wc] = q; }
;     __device__ __forceinline__ void operator()(const f32x4 (&acc)[2][2][4][2], const Unit& u, int wr, int wc, int fr, int fq) const {
;     ...
;                     for (int bj = 0; bj < 2; ++bj) { const u32x4 t = hv[ai][m][bj];
;                         r[m][bj][0] = (f32x4){__uint_as_float(t.x << 16), __uint_as_float(t.x & 0xffff0000u), __uint_as_float(t.y << 16), __uint_as_float(t.y & 0xffff0000u)};
;                         r[m][bj][1] = (f32x4){__uint_as_float(t.z << 16), __uint_as_float(t.z & 0xffff0000u), __uint_as_float(t.w << 16), __uint_as_float(t.w & 0xffff0000u)}; }
	v_lshlrev_b32_e32 v226, 16, v218
	v_and_b32_e32 v227, 0xffff0000, v218
	v_lshlrev_b32_e32 v218, 16, v219
	v_and_b32_e32 v219, 0xffff0000, v219
	v_lshlrev_b32_e32 v228, 16, v220
	v_and_b32_e32 v229, 0xffff0000, v220
	v_lshlrev_b32_e32 v220, 16, v221
	v_and_b32_e32 v221, 0xffff0000, v221
	v_pk_add_f32 v[128:129], v[128:129], v[218:219]
	v_pk_add_f32 v[126:127], v[126:127], v[226:227]
	v_pk_add_f32 v[218:219], v[124:125], v[220:221]
	v_pk_add_f32 v[124:125], v[122:123], v[228:229]
	v_mul_f32_e32 v122, v127, v127
	v_mul_f32_e32 v123, v129, v129
	v_fmac_f32_e32 v122, v126, v126
	v_fmac_f32_e32 v123, v128, v128
	v_add_f32_e32 v122, v122, v123
	v_mul_f32_e32 v123, v125, v125
	v_fmac_f32_e32 v123, v124, v124
	v_lshlrev_b32_e32 v238, 16, v222
	v_and_b32_e32 v239, 0xffff0000, v222
	v_lshlrev_b32_e32 v222, 16, v223
	v_and_b32_e32 v223, 0xffff0000, v223
	v_add_f32_e32 v122, v123, v122
	v_mul_f32_e32 v123, v219, v219
	v_lshlrev_b32_e32 v240, 16, v224
	v_and_b32_e32 v241, 0xffff0000, v224
	v_fmac_f32_e32 v123, v218, v218
	v_pk_add_f32 v[120:121], v[120:121], v[222:223]
	v_pk_add_f32 v[118:119], v[118:119], v[238:239]
	v_add_f32_e32 v217, v123, v122
	v_cvt_pk_bf16_f32 v122, v126, v127
	v_cvt_pk_bf16_f32 v123, v128, v129
	v_pk_add_f32 v[128:129], v[114:115], v[240:241]
	v_mul_f32_e32 v114, v119, v119
	v_mul_f32_e32 v115, v121, v121
	v_fmac_f32_e32 v114, v118, v118
	v_fmac_f32_e32 v115, v120, v120
	v_lshlrev_b32_e32 v224, 16, v225
	v_and_b32_e32 v225, 0xffff0000, v225
	v_add_f32_e32 v114, v114, v115
	v_mul_f32_e32 v115, v129, v129
	v_pk_add_f32 v[126:127], v[116:117], v[224:225]
	v_fmac_f32_e32 v115, v128, v128
	v_add_f32_e32 v114, v115, v114
	v_mul_f32_e32 v115, v127, v127
	v_fmac_f32_e32 v115, v126, v126
	v_add_f32_e32 v114, v115, v114
	v_add_f32_e32 v117, v217, v114
	v_mov_b32_e32 v217, v117
	v_mov_b32_e32 v247, v117
	s_nop 1
	v_permlane16_swap_b32_e32 v247, v217
	v_lshl_add_u64 v[114:115], s[40:41], 0, v[212:213]
	v_lshl_add_u64 v[210:211], v[114:115], 0, v[210:211]
	v_cvt_pk_bf16_f32 v124, v124, v125
	v_cvt_pk_bf16_f32 v125, v218, v219
	s_waitcnt lgkmcnt(0)
	v_add_f32_e32 v114, v117, v217
	v_mov_b32_e32 v115, v114
	v_mov_b32_e32 v247, v114
	s_nop 1
	v_permlane32_swap_b32_e32 v247, v115
	global_store_dwordx4 v[210:211], v[122:125], off
	v_cvt_pk_bf16_f32 v116, v118, v119
	v_cvt_pk_bf16_f32 v117, v120, v121
	v_cvt_pk_bf16_f32 v118, v128, v129
	v_cvt_pk_bf16_f32 v119, v126, v127
	global_store_dwordx4 v[210:211], v[116:119], off offset:256
	s_and_saveexec_b64 s[62:63], s[58:59]
	s_cbranch_execz .LBB0_383
	v_lshlrev_b64 v[116:117], 6, v[208:209]
	v_lshl_add_u64 v[116:117], s[42:43], 0, v[116:117]
	v_lshl_add_u64 v[116:117], s[60:61], 2, v[116:117]
	s_lshl_b32 s70, s87, 2
	v_lshl_add_u64 v[116:117], v[116:117], 0, s[70:71]
	s_waitcnt lgkmcnt(0)
	v_add_f32_e32 v114, v114, v115
	global_store_dword v[116:117], v114, off
.LBB0_383:
	s_or_b64 exec, exec, s[62:63]
	v_lshlrev_b32_e32 v116, 16, v182
	v_and_b32_e32 v117, 0xffff0000, v182
	v_lshlrev_b32_e32 v118, 16, v183
	v_and_b32_e32 v119, 0xffff0000, v183
	v_lshlrev_b32_e32 v120, 16, v184
	v_and_b32_e32 v121, 0xffff0000, v184
	v_lshlrev_b32_e32 v122, 16, v185
	v_and_b32_e32 v123, 0xffff0000, v185
	v_pk_add_f32 v[112:113], v[112:113], v[118:119]
	v_pk_add_f32 v[110:111], v[110:111], v[116:117]
	v_pk_add_f32 v[116:117], v[108:109], v[122:123]
	v_pk_add_f32 v[108:109], v[106:107], v[120:121]
	v_mul_f32_e32 v106, v111, v111
	v_mul_f32_e32 v107, v113, v113
	v_fmac_f32_e32 v106, v110, v110
	v_fmac_f32_e32 v107, v112, v112
	v_add_f32_e32 v106, v106, v107
	v_mul_f32_e32 v107, v109, v109
	v_fmac_f32_e32 v107, v108, v108
	v_lshlrev_b32_e32 v124, 16, v178
	v_and_b32_e32 v125, 0xffff0000, v178
	v_lshlrev_b32_e32 v126, 16, v179
	v_and_b32_e32 v127, 0xffff0000, v179
	v_add_f32_e32 v106, v107, v106
	v_mul_f32_e32 v107, v117, v117
	v_lshlrev_b32_e32 v128, 16, v180
	v_and_b32_e32 v129, 0xffff0000, v180
	v_fmac_f32_e32 v107, v116, v116
	v_pk_add_f32 v[104:105], v[104:105], v[126:127]
	v_pk_add_f32 v[102:103], v[102:103], v[124:125]
	v_add_f32_e32 v118, v107, v106
	v_cvt_pk_bf16_f32 v106, v110, v111
	v_cvt_pk_bf16_f32 v107, v112, v113
	v_cvt_pk_bf16_f32 v108, v108, v109
	v_cvt_pk_bf16_f32 v109, v116, v117
	v_pk_add_f32 v[116:117], v[98:99], v[128:129]
	v_mul_f32_e32 v98, v103, v103
	v_mul_f32_e32 v99, v105, v105
	v_fmac_f32_e32 v98, v102, v102
	v_fmac_f32_e32 v99, v104, v104
	v_lshlrev_b32_e32 v178, 16, v181
	v_and_b32_e32 v179, 0xffff0000, v181
	v_add_f32_e32 v98, v98, v99
	v_mul_f32_e32 v99, v117, v117
	v_pk_add_f32 v[112:113], v[100:101], v[178:179]
	v_fmac_f32_e32 v99, v116, v116
	v_add_f32_e32 v98, v99, v98
	v_mul_f32_e32 v99, v113, v113
	v_fmac_f32_e32 v99, v112, v112
	v_add_f32_e32 v98, v99, v98
	v_add_f32_e32 v101, v118, v98
	s_or_b32 s53, s51, 16
	v_mov_b32_e32 v118, v101
	v_mov_b32_e32 v247, v101
	s_nop 1
	v_permlane16_swap_b32_e32 v247, v118
	v_add_u32_e32 v114, s53, v216
	s_waitcnt lgkmcnt(1)
	v_ashrrev_i32_e32 v115, 31, v114
	v_lshlrev_b64 v[110:111], 11, v[114:115]
	v_lshl_add_u64 v[98:99], s[40:41], 0, v[110:111]
	v_lshl_add_u64 v[110:111], v[206:207], 1, v[98:99]
	s_waitcnt lgkmcnt(0)
	v_add_f32_e32 v98, v101, v118
	v_mov_b32_e32 v99, v98
	v_mov_b32_e32 v247, v98
	s_nop 1
	v_permlane32_swap_b32_e32 v247, v99
	global_store_dwordx4 v[110:111], v[106:109], off
	v_cvt_pk_bf16_f32 v100, v102, v103
	v_cvt_pk_bf16_f32 v101, v104, v105
	v_cvt_pk_bf16_f32 v102, v116, v117
	v_cvt_pk_bf16_f32 v103, v112, v113
	global_store_dwordx4 v[110:111], v[100:103], off offset:256
	s_and_saveexec_b64 s[62:63], s[58:59]
	s_cbranch_execz .LBB0_385
	v_lshlrev_b64 v[100:101], 6, v[114:115]
	v_lshl_add_u64 v[100:101], s[42:43], 0, v[100:101]
	v_lshl_add_u64 v[100:101], s[60:61], 2, v[100:101]
	s_lshl_b32 s70, s87, 2
	v_lshl_add_u64 v[100:101], v[100:101], 0, s[70:71]
	s_waitcnt lgkmcnt(0)
	v_add_f32_e32 v98, v98, v99
	global_store_dword v[100:101], v98, off
; __device__ __forceinline__ unsigned cvt_pk_bf16(float lo, float hi) { unsigned r; asm volatile("v_cvt_pk_bf16_f32 %0, %1, %2" : "=v"(r) : "v"(lo), "v"(hi)); return r; }
;     __device__ __forceinline__ void finish_half(const f32x4 (&acc)[2][2][4][2], const f32x4 (&r)[4][2][2], const Unit& u, int ai, int rl0, int col0, int wc, int fq) const {
;     ...
;         for (int m = 0; m < 4; ++m) { const size_t row = (size_t)(u.pm * BM + rl0 + ai * HALF + m * 16); const size_t off = row * 1024 + col0; float q = 0.f;
; #pragma unroll
;             for (int bj = 0; bj < 2; ++bj) {
;                 const f32x4 v0 = acc[ai][bj][m][0] + r[m][bj][0], v1 = acc[ai][bj][m][1] + r[m][bj][1];
;                 if (out32) { *(f32x4*)(out32 + off + bj * HALF) = v0; *(f32x4*)(out32 + off + bj * HALF + 4) = v1; }
;                 q += (v0[0] * v0[0] + v0[1] * v0[1]) + (v0[2] * v0[2] + v0[3] * v0[3]) + (v1[0] * v1[0] + v1[1] * v1[1]) + (v1[2] * v1[2] + v1[3] * v1[3]);
;                 u32x4 w; w.x = cvt_pk_bf16(v0[0], v0[1]); w.y = cvt_pk_bf16(v0[2], v0[3]); w.z = cvt_pk_bf16(v1[0], v1[1]); w.w = cvt_pk_bf16(v1[2], v1[3]);
;                 *(u32x4*)(hb + off + bj * HALF) = w; }
;             q += __shfl_xor(q, 16); q += __shfl_xor(q, 32);
;             if (fq == 0) ssq[row * 16 + u.pn * 4 + wc] = q; }
;     __device__ __forceinline__ void operator()(const f32x4 (&acc)[2][2][4][2], const Unit& u, int wr, int wc, int fr, int fq) const {
;     ...
;                     for (int bj = 0; bj < 2; ++bj) { const u32x4 t = hv[ai][m][bj];
;                         r[m][bj][0] = (f32x4){__uint_as_float(t.x << 16), __uint_as_float(t.x & 0xffff0000u), __uint_as_float(t.y << 16), __uint_as_float(t.y & 0xffff0000u)};
;                         r[m][bj][1] = (f32x4){__uint_as_float(t.z << 16), __uint_as_float(t.z & 0xffff0000u), __uint_as_float(t.w << 16), __uint_as_float(t.w & 0xffff0000u)}; }
.LBB0_385:
	s_or_b64 exec, exec, s[62:63]
	v_lshlrev_b32_e32 v100, 16, v174
	v_and_b32_e32 v101, 0xffff0000, v174
	v_lshlrev_b32_e32 v102, 16, v175
	v_and_b32_e32 v103, 0xffff0000, v175
	v_lshlrev_b32_e32 v104, 16, v176
	v_and_b32_e32 v105, 0xffff0000, v176
	v_lshlrev_b32_e32 v106, 16, v177
	v_and_b32_e32 v107, 0xffff0000, v177
	v_pk_add_f32 v[96:97], v[96:97], v[102:103]
	v_pk_add_f32 v[94:95], v[94:95], v[100:101]
	v_pk_add_f32 v[100:101], v[92:93], v[106:107]
	v_pk_add_f32 v[92:93], v[90:91], v[104:105]
	v_mul_f32_e32 v90, v95, v95
	v_mul_f32_e32 v91, v97, v97
	v_fmac_f32_e32 v90, v94, v94
	v_fmac_f32_e32 v91, v96, v96
	v_add_f32_e32 v90, v90, v91
	v_mul_f32_e32 v91, v93, v93
	v_fmac_f32_e32 v91, v92, v92
	v_lshlrev_b32_e32 v108, 16, v170
	v_and_b32_e32 v109, 0xffff0000, v170
	v_lshlrev_b32_e32 v110, 16, v171
	v_and_b32_e32 v111, 0xffff0000, v171
	v_add_f32_e32 v90, v91, v90
	v_mul_f32_e32 v91, v101, v101
	v_lshlrev_b32_e32 v112, 16, v172
	v_and_b32_e32 v113, 0xffff0000, v172
	v_fmac_f32_e32 v91, v100, v100
	v_pk_add_f32 v[88:89], v[88:89], v[110:111]
	v_pk_add_f32 v[86:87], v[86:87], v[108:109]
	v_add_f32_e32 v102, v91, v90
	v_cvt_pk_bf16_f32 v90, v94, v95
	v_cvt_pk_bf16_f32 v91, v96, v97
	v_cvt_pk_bf16_f32 v92, v92, v93
	v_cvt_pk_bf16_f32 v93, v100, v101
	v_pk_add_f32 v[100:101], v[82:83], v[112:113]
	v_mul_f32_e32 v82, v87, v87
	v_mul_f32_e32 v83, v89, v89
	v_fmac_f32_e32 v82, v86, v86
	v_fmac_f32_e32 v83, v88, v88
	v_lshlrev_b32_e32 v114, 16, v173
	v_and_b32_e32 v115, 0xffff0000, v173
	v_add_f32_e32 v82, v82, v83
	v_mul_f32_e32 v83, v101, v101
	v_pk_add_f32 v[96:97], v[84:85], v[114:115]
	v_fmac_f32_e32 v83, v100, v100
	v_add_f32_e32 v82, v83, v82
	v_mul_f32_e32 v83, v97, v97
	v_fmac_f32_e32 v83, v96, v96
	v_add_f32_e32 v82, v83, v82
	v_add_f32_e32 v85, v102, v82
	s_or_b32 s80, s51, 32
	v_mov_b32_e32 v102, v85
	v_mov_b32_e32 v247, v85
	s_nop 1
	v_permlane16_swap_b32_e32 v247, v102
	v_add_u32_e32 v98, s80, v216
	s_waitcnt lgkmcnt(1)
	v_ashrrev_i32_e32 v99, 31, v98
	v_lshlrev_b64 v[94:95], 11, v[98:99]
	v_lshl_add_u64 v[82:83], s[40:41], 0, v[94:95]
	v_lshl_add_u64 v[94:95], v[206:207], 1, v[82:83]
	s_waitcnt lgkmcnt(0)
	v_add_f32_e32 v82, v85, v102
	v_mov_b32_e32 v83, v82
	v_mov_b32_e32 v247, v82
	s_nop 1
	v_permlane32_swap_b32_e32 v247, v83
	global_store_dwordx4 v[94:95], v[90:93], off
	v_cvt_pk_bf16_f32 v84, v86, v87
	v_cvt_pk_bf16_f32 v85, v88, v89
	v_cvt_pk_bf16_f32 v86, v100, v101
	v_cvt_pk_bf16_f32 v87, v96, v97
	global_store_dwordx4 v[94:95], v[84:87], off offset:256
	s_and_saveexec_b64 s[62:63], s[58:59]
	s_cbranch_execz .LBB0_387
	v_lshlrev_b64 v[84:85], 6, v[98:99]
	v_lshl_add_u64 v[84:85], s[42:43], 0, v[84:85]
	v_lshl_add_u64 v[84:85], s[60:61], 2, v[84:85]
	s_lshl_b32 s70, s87, 2
	v_lshl_add_u64 v[84:85], v[84:85], 0, s[70:71]
	s_waitcnt lgkmcnt(0)
	v_add_f32_e32 v82, v82, v83
	global_store_dword v[84:85], v82, off
.LBB0_387:
	s_or_b64 exec, exec, s[62:63]
	v_lshlrev_b32_e32 v84, 16, v166
	v_and_b32_e32 v85, 0xffff0000, v166
	v_lshlrev_b32_e32 v86, 16, v167
	v_and_b32_e32 v87, 0xffff0000, v167
	v_lshlrev_b32_e32 v88, 16, v168
	v_and_b32_e32 v89, 0xffff0000, v168
	v_lshlrev_b32_e32 v90, 16, v169
	v_and_b32_e32 v91, 0xffff0000, v169
	v_pk_add_f32 v[80:81], v[80:81], v[86:87]
	v_pk_add_f32 v[78:79], v[78:79], v[84:85]
	v_pk_add_f32 v[84:85], v[76:77], v[90:91]
	v_pk_add_f32 v[76:77], v[74:75], v[88:89]
	v_mul_f32_e32 v74, v79, v79
	v_mul_f32_e32 v75, v81, v81
	v_fmac_f32_e32 v74, v78, v78
	v_fmac_f32_e32 v75, v80, v80
	v_add_f32_e32 v74, v74, v75
	v_mul_f32_e32 v75, v77, v77
	v_fmac_f32_e32 v75, v76, v76
	v_lshlrev_b32_e32 v92, 16, v162
	v_and_b32_e32 v93, 0xffff0000, v162
	v_lshlrev_b32_e32 v94, 16, v163
	v_and_b32_e32 v95, 0xffff0000, v163
	v_add_f32_e32 v74, v75, v74
	v_mul_f32_e32 v75, v85, v85
	v_lshlrev_b32_e32 v96, 16, v164
	v_and_b32_e32 v97, 0xffff0000, v164
	v_fmac_f32_e32 v75, v84, v84
	v_pk_add_f32 v[72:73], v[72:73], v[94:95]
	v_pk_add_f32 v[70:71], v[70:71], v[92:93]
	v_add_f32_e32 v86, v75, v74
	v_cvt_pk_bf16_f32 v74, v78, v79
	v_cvt_pk_bf16_f32 v75, v80, v81
	v_cvt_pk_bf16_f32 v76, v76, v77
	v_cvt_pk_bf16_f32 v77, v84, v85
	v_pk_add_f32 v[84:85], v[66:67], v[96:97]
	v_mul_f32_e32 v66, v71, v71
	v_mul_f32_e32 v67, v73, v73
	v_fmac_f32_e32 v66, v70, v70
	v_fmac_f32_e32 v67, v72, v72
	v_lshlrev_b32_e32 v98, 16, v165
	v_and_b32_e32 v99, 0xffff0000, v165
	v_add_f32_e32 v66, v66, v67
	v_mul_f32_e32 v67, v85, v85
	v_pk_add_f32 v[80:81], v[68:69], v[98:99]
	v_fmac_f32_e32 v67, v84, v84
	v_add_f32_e32 v66, v67, v66
	v_mul_f32_e32 v67, v81, v81
	v_fmac_f32_e32 v67, v80, v80
	v_add_f32_e32 v66, v67, v66
	v_add_f32_e32 v69, v86, v66
	s_or_b32 s81, s51, 48
	v_mov_b32_e32 v86, v69
	v_mov_b32_e32 v247, v69
	s_nop 1
	v_permlane16_swap_b32_e32 v247, v86
	v_add_u32_e32 v82, s81, v216
	s_waitcnt lgkmcnt(1)
	v_ashrrev_i32_e32 v83, 31, v82
	v_lshlrev_b64 v[78:79], 11, v[82:83]
	v_lshl_add_u64 v[66:67], s[40:41], 0, v[78:79]
	v_lshl_add_u64 v[78:79], v[206:207], 1, v[66:67]
	s_waitcnt lgkmcnt(0)
	v_add_f32_e32 v66, v69, v86
	v_mov_b32_e32 v67, v66
	v_mov_b32_e32 v247, v66
	s_nop 1
	v_permlane32_swap_b32_e32 v247, v67
	global_store_dwordx4 v[78:79], v[74:77], off
	v_cvt_pk_bf16_f32 v68, v70, v71
	v_cvt_pk_bf16_f32 v69, v72, v73
	v_cvt_pk_bf16_f32 v70, v84, v85
	v_cvt_pk_bf16_f32 v71, v80, v81
	global_store_dwordx4 v[78:79], v[68:71], off offset:256
	s_and_saveexec_b64 s[62:63], s[58:59]
	s_cbranch_execz .LBB0_389
	v_lshlrev_b64 v[68:69], 6, v[82:83]
	v_lshl_add_u64 v[68:69], s[42:43], 0, v[68:69]
	v_lshl_add_u64 v[68:69], s[60:61], 2, v[68:69]
	s_lshl_b32 s70, s87, 2
	v_lshl_add_u64 v[68:69], v[68:69], 0, s[70:71]
	s_waitcnt lgkmcnt(0)
	v_add_f32_e32 v66, v66, v67
	global_store_dword v[68:69], v66, off
; __device__ __forceinline__ unsigned cvt_pk_bf16(float lo, float hi) { unsigned r; asm volatile("v_cvt_pk_bf16_f32 %0, %1, %2" : "=v"(r) : "v"(lo), "v"(hi)); return r; }
;     __device__ __forceinline__ void finish_half(const f32x4 (&acc)[2][2][4][2], const f32x4 (&r)[4][2][2], const Unit& u, int ai, int rl0, int col0, int wc, int fq) const {
;     ...
;         for (int m = 0; m < 4; ++m) { const size_t row = (size_t)(u.pm * BM + rl0 + ai * HALF + m * 16); const size_t off = row * 1024 + col0; float q = 0.f;
; #pragma unroll
;             for (int bj = 0; bj < 2; ++bj) {
;                 const f32x4 v0 = acc[ai][bj][m][0] + r[m][bj][0], v1 = acc[ai][bj][m][1] + r[m][bj][1];
;                 if (out32) { *(f32x4*)(out32 + off + bj * HALF) = v0; *(f32x4*)(out32 + off + bj * HALF + 4) = v1; }
;                 q += (v0[0] * v0[0] + v0[1] * v0[1]) + (v0[2] * v0[2] + v0[3] * v0[3]) + (v1[0] * v1[0] + v1[1] * v1[1]) + (v1[2] * v1[2] + v1[3] * v1[3]);
;                 u32x4 w; w.x = cvt_pk_bf16(v0[0], v0[1]); w.y = cvt_pk_bf16(v0[2], v0[3]); w.z = cvt_pk_bf16(v1[0], v1[1]); w.w = cvt_pk_bf16(v1[2], v1[3]);
;                 *(u32x4*)(hb + off + bj * HALF) = w; }
;             q += __shfl_xor(q, 16); q += __shfl_xor(q, 32);
;             if (fq == 0) ssq[row * 16 + u.pn * 4 + wc] = q; }
;     __device__ __forceinline__ void operator()(const f32x4 (&acc)[2][2][4][2], const Unit& u, int wr, int wc, int fr, int fq) const {
;     ...
;                     for (int bj = 0; bj < 2; ++bj) { const u32x4 t = hv[ai][m][bj];
;                         r[m][bj][0] = (f32x4){__uint_as_float(t.x << 16), __uint_as_float(t.x & 0xffff0000u), __uint_as_float(t.y << 16), __uint_as_float(t.y & 0xffff0000u)};
;                         r[m][bj][1] = (f32x4){__uint_as_float(t.z << 16), __uint_as_float(t.z & 0xffff0000u), __uint_as_float(t.w << 16), __uint_as_float(t.w & 0xffff0000u)}; }
.LBB0_389:
	s_or_b64 exec, exec, s[62:63]
	v_lshlrev_b32_e32 v70, 16, v158
	v_and_b32_e32 v71, 0xffff0000, v158
	v_lshlrev_b32_e32 v72, 16, v159
	v_and_b32_e32 v73, 0xffff0000, v159
	v_lshlrev_b32_e32 v74, 16, v160
	v_and_b32_e32 v75, 0xffff0000, v160
	v_lshlrev_b32_e32 v76, 16, v161
	v_and_b32_e32 v77, 0xffff0000, v161
	v_pk_add_f32 v[64:65], v[64:65], v[72:73]
	v_pk_add_f32 v[62:63], v[62:63], v[70:71]
	v_pk_add_f32 v[70:71], v[60:61], v[76:77]
	v_pk_add_f32 v[60:61], v[58:59], v[74:75]
	v_mul_f32_e32 v58, v63, v63
	v_mul_f32_e32 v59, v65, v65
	v_fmac_f32_e32 v58, v62, v62
	v_fmac_f32_e32 v59, v64, v64
	v_add_f32_e32 v58, v58, v59
	v_mul_f32_e32 v59, v61, v61
	v_fmac_f32_e32 v59, v60, v60
	v_lshlrev_b32_e32 v78, 16, v154
	v_and_b32_e32 v79, 0xffff0000, v154
	v_lshlrev_b32_e32 v80, 16, v155
	v_and_b32_e32 v81, 0xffff0000, v155
	v_add_f32_e32 v58, v59, v58
	v_mul_f32_e32 v59, v71, v71
	v_lshlrev_b32_e32 v82, 16, v156
	v_and_b32_e32 v83, 0xffff0000, v156
	v_fmac_f32_e32 v59, v70, v70
	v_pk_add_f32 v[56:57], v[56:57], v[80:81]
	v_pk_add_f32 v[54:55], v[54:55], v[78:79]
	v_add_f32_e32 v69, v59, v58
	v_cvt_pk_bf16_f32 v58, v62, v63
	v_cvt_pk_bf16_f32 v59, v64, v65
	v_cvt_pk_bf16_f32 v60, v60, v61
	v_cvt_pk_bf16_f32 v61, v70, v71
	v_pk_add_f32 v[70:71], v[50:51], v[82:83]
	v_mul_f32_e32 v50, v55, v55
	v_mul_f32_e32 v51, v57, v57
	v_fmac_f32_e32 v50, v54, v54
	v_fmac_f32_e32 v51, v56, v56
	v_lshlrev_b32_e32 v84, 16, v157
	v_and_b32_e32 v85, 0xffff0000, v157
	v_add_f32_e32 v50, v50, v51
	v_mul_f32_e32 v51, v71, v71
	v_pk_add_f32 v[64:65], v[52:53], v[84:85]
	v_fmac_f32_e32 v51, v70, v70
	v_add_f32_e32 v50, v51, v50
	v_mul_f32_e32 v51, v65, v65
	v_fmac_f32_e32 v51, v64, v64
	v_add_f32_e32 v50, v51, v50
	v_add_f32_e32 v53, v69, v50
	v_add_u32_e32 v68, 0x80, v216
	v_mov_b32_e32 v69, v53
	v_mov_b32_e32 v247, v53
	s_nop 1
	v_permlane16_swap_b32_e32 v247, v69
	v_add_u32_e32 v66, s51, v68
	s_waitcnt lgkmcnt(1)
	v_ashrrev_i32_e32 v67, 31, v66
	v_lshlrev_b64 v[62:63], 11, v[66:67]
	v_lshl_add_u64 v[50:51], s[40:41], 0, v[62:63]
	v_lshl_add_u64 v[62:63], v[206:207], 1, v[50:51]
	s_waitcnt lgkmcnt(0)
	v_add_f32_e32 v50, v53, v69
	v_mov_b32_e32 v51, v50
	v_mov_b32_e32 v247, v50
	s_nop 1
	v_permlane32_swap_b32_e32 v247, v51
	global_store_dwordx4 v[62:63], v[58:61], off
	v_cvt_pk_bf16_f32 v52, v54, v55
	v_cvt_pk_bf16_f32 v53, v56, v57
	v_cvt_pk_bf16_f32 v54, v70, v71
	v_cvt_pk_bf16_f32 v55, v64, v65
	global_store_dwordx4 v[62:63], v[52:55], off offset:256
	s_and_saveexec_b64 s[62:63], s[58:59]
	s_cbranch_execz .LBB0_391
	v_lshlrev_b64 v[52:53], 6, v[66:67]
	v_lshl_add_u64 v[52:53], s[42:43], 0, v[52:53]
	v_lshl_add_u64 v[52:53], s[60:61], 2, v[52:53]
	s_lshl_b32 s70, s87, 2
	v_lshl_add_u64 v[52:53], v[52:53], 0, s[70:71]
	s_waitcnt lgkmcnt(0)
	v_add_f32_e32 v50, v50, v51
	global_store_dword v[52:53], v50, off
.LBB0_391:
	s_or_b64 exec, exec, s[62:63]
	v_lshlrev_b32_e32 v52, 16, v150
	v_and_b32_e32 v53, 0xffff0000, v150
	v_lshlrev_b32_e32 v54, 16, v151
	v_and_b32_e32 v55, 0xffff0000, v151
	v_lshlrev_b32_e32 v56, 16, v152
	v_and_b32_e32 v57, 0xffff0000, v152
	v_lshlrev_b32_e32 v58, 16, v153
	v_and_b32_e32 v59, 0xffff0000, v153
	v_pk_add_f32 v[48:49], v[48:49], v[54:55]
	v_pk_add_f32 v[46:47], v[46:47], v[52:53]
	v_pk_add_f32 v[52:53], v[44:45], v[58:59]
	v_pk_add_f32 v[44:45], v[42:43], v[56:57]
	v_mul_f32_e32 v42, v47, v47
	v_mul_f32_e32 v43, v49, v49
	v_fmac_f32_e32 v42, v46, v46
	v_fmac_f32_e32 v43, v48, v48
	v_add_f32_e32 v42, v42, v43
	v_mul_f32_e32 v43, v45, v45
	v_fmac_f32_e32 v43, v44, v44
	v_lshlrev_b32_e32 v60, 16, v146
	v_and_b32_e32 v61, 0xffff0000, v146
	v_lshlrev_b32_e32 v62, 16, v147
	v_and_b32_e32 v63, 0xffff0000, v147
	v_add_f32_e32 v42, v43, v42
	v_mul_f32_e32 v43, v53, v53
	v_lshlrev_b32_e32 v64, 16, v148
	v_and_b32_e32 v65, 0xffff0000, v148
	v_fmac_f32_e32 v43, v52, v52
	v_pk_add_f32 v[40:41], v[40:41], v[62:63]
	v_pk_add_f32 v[38:39], v[38:39], v[60:61]
	v_add_f32_e32 v54, v43, v42
	v_cvt_pk_bf16_f32 v42, v46, v47
	v_cvt_pk_bf16_f32 v43, v48, v49
	v_cvt_pk_bf16_f32 v44, v44, v45
	v_cvt_pk_bf16_f32 v45, v52, v53
	v_pk_add_f32 v[52:53], v[34:35], v[64:65]
	v_mul_f32_e32 v34, v39, v39
	v_mul_f32_e32 v35, v41, v41
	v_fmac_f32_e32 v34, v38, v38
	v_fmac_f32_e32 v35, v40, v40
	v_lshlrev_b32_e32 v66, 16, v149
	v_and_b32_e32 v67, 0xffff0000, v149
	v_add_f32_e32 v34, v34, v35
	v_mul_f32_e32 v35, v53, v53
	v_pk_add_f32 v[48:49], v[36:37], v[66:67]
	v_fmac_f32_e32 v35, v52, v52
	v_add_f32_e32 v34, v35, v34
	v_mul_f32_e32 v35, v49, v49
	v_fmac_f32_e32 v35, v48, v48
	v_add_f32_e32 v34, v35, v34
	v_add_f32_e32 v37, v54, v34
	v_mov_b32_e32 v54, v37
	v_mov_b32_e32 v247, v37
	s_nop 1
	v_permlane16_swap_b32_e32 v247, v54
	v_add_u32_e32 v50, s53, v68
	s_waitcnt lgkmcnt(1)
	v_ashrrev_i32_e32 v51, 31, v50
	v_lshlrev_b64 v[46:47], 11, v[50:51]
	v_lshl_add_u64 v[34:35], s[40:41], 0, v[46:47]
	v_lshl_add_u64 v[46:47], v[206:207], 1, v[34:35]
	s_waitcnt lgkmcnt(0)
	v_add_f32_e32 v34, v37, v54
	v_mov_b32_e32 v35, v34
	v_mov_b32_e32 v247, v34
	s_nop 1
	v_permlane32_swap_b32_e32 v247, v35
	global_store_dwordx4 v[46:47], v[42:45], off
	v_cvt_pk_bf16_f32 v36, v38, v39
	v_cvt_pk_bf16_f32 v37, v40, v41
	v_cvt_pk_bf16_f32 v38, v52, v53
	v_cvt_pk_bf16_f32 v39, v48, v49
	global_store_dwordx4 v[46:47], v[36:39], off offset:256
	s_and_saveexec_b64 s[62:63], s[58:59]
	s_cbranch_execz .LBB0_393
	v_lshlrev_b64 v[36:37], 6, v[50:51]
	v_lshl_add_u64 v[36:37], s[42:43], 0, v[36:37]
	v_lshl_add_u64 v[36:37], s[60:61], 2, v[36:37]
	s_lshl_b32 s70, s87, 2
	v_lshl_add_u64 v[36:37], v[36:37], 0, s[70:71]
	s_waitcnt lgkmcnt(0)
	v_add_f32_e32 v34, v34, v35
	global_store_dword v[36:37], v34, off
; __device__ __forceinline__ unsigned cvt_pk_bf16(float lo, float hi) { unsigned r; asm volatile("v_cvt_pk_bf16_f32 %0, %1, %2" : "=v"(r) : "v"(lo), "v"(hi)); return r; }
;     __device__ __forceinline__ void finish_half(const f32x4 (&acc)[2][2][4][2], const f32x4 (&r)[4][2][2], const Unit& u, int ai, int rl0, int col0, int wc, int fq) const {
;     ...
;         for (int m = 0; m < 4; ++m) { const size_t row = (size_t)(u.pm * BM + rl0 + ai * HALF + m * 16); const size_t off = row * 1024 + col0; float q = 0.f;
; #pragma unroll
;             for (int bj = 0; bj < 2; ++bj) {
;                 const f32x4 v0 = acc[ai][bj][m][0] + r[m][bj][0], v1 = acc[ai][bj][m][1] + r[m][bj][1];
;                 if (out32) { *(f32x4*)(out32 + off + bj * HALF) = v0; *(f32x4*)(out32 + off + bj * HALF + 4) = v1; }
;                 q += (v0[0] * v0[0] + v0[1] * v0[1]) + (v0[2] * v0[2] + v0[3] * v0[3]) + (v1[0] * v1[0] + v1[1] * v1[1]) + (v1[2] * v1[2] + v1[3] * v1[3]);
;                 u32x4 w; w.x = cvt_pk_bf16(v0[0], v0[1]); w.y = cvt_pk_bf16(v0[2], v0[3]); w.z = cvt_pk_bf16(v1[0], v1[1]); w.w = cvt_pk_bf16(v1[2], v1[3]);
;                 *(u32x4*)(hb + off + bj * HALF) = w; }
;             q += __shfl_xor(q, 16); q += __shfl_xor(q, 32);
;             if (fq == 0) ssq[row * 16 + u.pn * 4 + wc] = q; }
;     __device__ __forceinline__ void operator()(const f32x4 (&acc)[2][2][4][2], const Unit& u, int wr, int wc, int fr, int fq) const {
;     ...
;                     for (int bj = 0; bj < 2; ++bj) { const u32x4 t = hv[ai][m][bj];
;                         r[m][bj][0] = (f32x4){__uint_as_float(t.x << 16), __uint_as_float(t.x & 0xffff0000u), __uint_as_float(t.y << 16), __uint_as_float(t.y & 0xffff0000u)};
;                         r[m][bj][1] = (f32x4){__uint_as_float(t.z << 16), __uint_as_float(t.z & 0xffff0000u), __uint_as_float(t.w << 16), __uint_as_float(t.w & 0xffff0000u)}; }
.LBB0_393:
	s_or_b64 exec, exec, s[62:63]
	v_lshlrev_b32_e32 v36, 16, v142
	v_and_b32_e32 v37, 0xffff0000, v142
	v_lshlrev_b32_e32 v38, 16, v143
	v_and_b32_e32 v39, 0xffff0000, v143
	v_lshlrev_b32_e32 v40, 16, v144
	v_and_b32_e32 v41, 0xffff0000, v144
	v_lshlrev_b32_e32 v42, 16, v145
	v_and_b32_e32 v43, 0xffff0000, v145
	v_pk_add_f32 v[32:33], v[32:33], v[38:39]
	v_pk_add_f32 v[30:31], v[30:31], v[36:37]
	v_pk_add_f32 v[36:37], v[28:29], v[42:43]
	v_pk_add_f32 v[28:29], v[26:27], v[40:41]
	v_mul_f32_e32 v26, v31, v31
	v_mul_f32_e32 v27, v33, v33
	v_fmac_f32_e32 v26, v30, v30
	v_fmac_f32_e32 v27, v32, v32
	v_add_f32_e32 v26, v26, v27
	v_mul_f32_e32 v27, v29, v29
	v_fmac_f32_e32 v27, v28, v28
	v_lshlrev_b32_e32 v44, 16, v138
	v_and_b32_e32 v45, 0xffff0000, v138
	v_lshlrev_b32_e32 v46, 16, v139
	v_and_b32_e32 v47, 0xffff0000, v139
	v_add_f32_e32 v26, v27, v26
	v_mul_f32_e32 v27, v37, v37
	v_lshlrev_b32_e32 v48, 16, v140
	v_and_b32_e32 v49, 0xffff0000, v140
	v_fmac_f32_e32 v27, v36, v36
	v_pk_add_f32 v[24:25], v[24:25], v[46:47]
	v_pk_add_f32 v[22:23], v[22:23], v[44:45]
	v_add_f32_e32 v38, v27, v26
	v_cvt_pk_bf16_f32 v26, v30, v31
	v_cvt_pk_bf16_f32 v27, v32, v33
	v_cvt_pk_bf16_f32 v28, v28, v29
	v_cvt_pk_bf16_f32 v29, v36, v37
	v_pk_add_f32 v[36:37], v[18:19], v[48:49]
	v_mul_f32_e32 v18, v23, v23
	v_mul_f32_e32 v19, v25, v25
	v_fmac_f32_e32 v18, v22, v22
	v_fmac_f32_e32 v19, v24, v24
	v_lshlrev_b32_e32 v50, 16, v141
	v_and_b32_e32 v51, 0xffff0000, v141
	v_add_f32_e32 v18, v18, v19
	v_mul_f32_e32 v19, v37, v37
	v_pk_add_f32 v[32:33], v[20:21], v[50:51]
	v_fmac_f32_e32 v19, v36, v36
	v_add_f32_e32 v18, v19, v18
	v_mul_f32_e32 v19, v33, v33
	v_fmac_f32_e32 v19, v32, v32
	v_add_f32_e32 v18, v19, v18
	v_add_f32_e32 v21, v38, v18
	v_mov_b32_e32 v38, v21
	v_mov_b32_e32 v247, v21
	s_nop 1
	v_permlane16_swap_b32_e32 v247, v38
	v_add_u32_e32 v34, s80, v68
	s_waitcnt lgkmcnt(1)
	v_ashrrev_i32_e32 v35, 31, v34
	v_lshlrev_b64 v[30:31], 11, v[34:35]
	v_lshl_add_u64 v[18:19], s[40:41], 0, v[30:31]
	v_lshl_add_u64 v[30:31], v[206:207], 1, v[18:19]
	s_waitcnt lgkmcnt(0)
	v_add_f32_e32 v18, v21, v38
	v_mov_b32_e32 v19, v18
	v_mov_b32_e32 v247, v18
	s_nop 1
	v_permlane32_swap_b32_e32 v247, v19
	global_store_dwordx4 v[30:31], v[26:29], off
	v_cvt_pk_bf16_f32 v20, v22, v23
	v_cvt_pk_bf16_f32 v21, v24, v25
	v_cvt_pk_bf16_f32 v22, v36, v37
	v_cvt_pk_bf16_f32 v23, v32, v33
	global_store_dwordx4 v[30:31], v[20:23], off offset:256
	s_and_saveexec_b64 s[62:63], s[58:59]
	s_cbranch_execz .LBB0_395
	v_lshlrev_b64 v[20:21], 6, v[34:35]
	v_lshl_add_u64 v[20:21], s[42:43], 0, v[20:21]
	v_lshl_add_u64 v[20:21], s[60:61], 2, v[20:21]
	s_lshl_b32 s70, s87, 2
	v_lshl_add_u64 v[20:21], v[20:21], 0, s[70:71]
	s_waitcnt lgkmcnt(0)
	v_add_f32_e32 v18, v18, v19
	global_store_dword v[20:21], v18, off
.LBB0_395:
	s_or_b64 exec, exec, s[62:63]
	v_lshlrev_b32_e32 v18, 16, v134
	s_waitcnt lgkmcnt(0)
	v_and_b32_e32 v19, 0xffff0000, v134
	v_lshlrev_b32_e32 v26, 16, v130
	v_and_b32_e32 v27, 0xffff0000, v130
	v_lshlrev_b32_e32 v20, 16, v135
	v_and_b32_e32 v21, 0xffff0000, v135
	v_lshlrev_b32_e32 v22, 16, v136
	v_and_b32_e32 v23, 0xffff0000, v136
	v_lshlrev_b32_e32 v24, 16, v137
	v_and_b32_e32 v25, 0xffff0000, v137
	v_lshlrev_b32_e32 v30, 16, v132
	v_and_b32_e32 v31, 0xffff0000, v132
	v_lshlrev_b32_e32 v32, 16, v133
	v_and_b32_e32 v33, 0xffff0000, v133
	v_pk_add_f32 v[14:15], v[14:15], v[18:19]
	v_pk_add_f32 v[6:7], v[6:7], v[26:27]
	v_lshlrev_b32_e32 v28, 16, v131
	v_and_b32_e32 v29, 0xffff0000, v131
	v_pk_add_f32 v[16:17], v[16:17], v[20:21]
	v_pk_add_f32 v[18:19], v[12:13], v[24:25]
	v_pk_add_f32 v[20:21], v[10:11], v[22:23]
	v_cvt_pk_bf16_f32 v10, v14, v15
	v_pk_add_f32 v[24:25], v[4:5], v[32:33]
	v_pk_add_f32 v[4:5], v[2:3], v[30:31]
	v_mov_b32_e32 v2, v14
	v_mov_b32_e32 v14, v15
	v_mov_b32_e32 v15, v7
	v_pk_add_f32 v[8:9], v[8:9], v[28:29]
	v_mov_b32_e32 v3, v6
	v_pk_mul_f32 v[14:15], v[14:15], v[14:15]
	v_cvt_pk_bf16_f32 v11, v16, v17
	v_add_u32_e32 v142, s81, v68
	v_pk_fma_f32 v[2:3], v[2:3], v[2:3], v[14:15]
	v_mov_b32_e32 v14, v16
	v_mov_b32_e32 v16, v17
	v_mov_b32_e32 v17, v9
	v_mov_b32_e32 v15, v8
	v_pk_mul_f32 v[16:17], v[16:17], v[16:17]
	v_ashrrev_i32_e32 v143, 31, v142
	v_pk_fma_f32 v[14:15], v[14:15], v[14:15], v[16:17]
	v_mov_b32_e32 v16, v21
	v_mov_b32_e32 v17, v5
	v_pk_add_f32 v[2:3], v[2:3], v[14:15]
	v_mov_b32_e32 v14, v20
	v_mov_b32_e32 v15, v4
	v_pk_mul_f32 v[16:17], v[16:17], v[16:17]
	v_lshlrev_b64 v[22:23], 11, v[142:143]
	v_pk_fma_f32 v[14:15], v[14:15], v[14:15], v[16:17]
	v_mov_b32_e32 v16, v19
	v_mov_b32_e32 v17, v25
	v_pk_add_f32 v[2:3], v[14:15], v[2:3]
	v_mov_b32_e32 v14, v18
	v_mov_b32_e32 v15, v24
	v_pk_mul_f32 v[16:17], v[16:17], v[16:17]
	v_cvt_pk_bf16_f32 v12, v20, v21
	v_cvt_pk_bf16_f32 v13, v18, v19
	s_nop 0
	v_pk_fma_f32 v[14:15], v[14:15], v[14:15], v[16:17]
	s_nop 0
	v_pk_add_f32 v[2:3], v[14:15], v[2:3]
	s_nop 0
	v_add_f32_e32 v16, v2, v3
	v_mov_b32_e32 v17, v16
	v_mov_b32_e32 v247, v16
	s_nop 1
	v_permlane16_swap_b32_e32 v247, v17
	v_lshl_add_u64 v[2:3], s[40:41], 0, v[22:23]
	v_lshl_add_u64 v[14:15], v[206:207], 1, v[2:3]
	global_store_dwordx4 v[14:15], v[10:13], off
	v_cvt_pk_bf16_f32 v2, v6, v7
	s_waitcnt lgkmcnt(0)
	v_add_f32_e32 v130, v16, v17
	v_mov_b32_e32 v131, v130
	v_mov_b32_e32 v247, v130
	s_nop 1
	v_permlane32_swap_b32_e32 v247, v131
	v_cvt_pk_bf16_f32 v3, v8, v9
	v_cvt_pk_bf16_f32 v4, v4, v5
	v_cvt_pk_bf16_f32 v5, v24, v25
	global_store_dwordx4 v[14:15], v[2:5], off offset:256
	s_and_saveexec_b64 s[62:63], s[58:59]
	s_cbranch_execz .LBB0_379

;     __device__ __forceinline__ void operator()(const f32x4 (&acc)[2][2][4][2], const Unit& u, int wr, int wc, int fr, int fq) const {
;     ...
;             u32x4 hv[2][4][2];
; #pragma unroll
;             for (int ai = 0; ai < 2; ++ai)
; #pragma unroll
;                 for (int m = 0; m < 4; ++m)
; #pragma unroll
;                     for (int bj = 0; bj < 2; ++bj) hv[ai][m][bj] = *(const u32x4*)(hb + (size_t)(u.pm * BM + rl0 + ai * HALF + m * 16) * 1024 + col0 + bj * HALF);
;             asm volatile("" ::: "memory");
.LBB0_570:
	v_mbcnt_lo_u32_b32 v246, -1, 0
	v_mbcnt_hi_u32_b32 v246, -1, v246
	v_and_b32_e32 v249, 3, v246
	v_lshrrev_b32_e32 v245, 4, v246
	v_sub_u32_e32 v245, v249, v245
	v_lshlrev_b32_e32 v245, 4, v245
	v_and_b32_e32 v244, 15, v246
	v_lshrrev_b32_e32 v249, 2, v246
	v_sub_u32_e32 v249, v249, v244
	v_lshl_add_u32 v244, v244, 2, 0
	v_lshrrev_b32_e32 v246, 4, v246
	v_add_u32_e32 v246, v244, v246
	v_lshlrev_b32_e32 v246, 2, v246
	v_lshl_add_u32 v244, v249, 11, v245
	v_ashrrev_i32_e32 v245, 31, v244
	s_lshl_b32 s43, s70, 8
	v_mov_b32_e32 v213, v193
	v_mov_b32_e32 v106, v195
	s_or_b32 s43, s43, s69
	s_mov_b32 s45, 0x8000
	v_add_u32_e32 v212, s68, v106
	v_lshl_add_u32 v206, v213, 3, s43
	s_lshl_b32 s43, s78, 8
	v_add_u32_e32 v208, s43, v212
	v_ashrrev_i32_e32 v207, 31, v206
	v_lshlrev_b64 v[222:223], 1, v[206:207]
	v_ashrrev_i32_e32 v209, 31, v208
	v_lshl_add_u64 v[106:107], s[28:29], 0, v[222:223]
	v_lshlrev_b64 v[224:225], 11, v[208:209]
	v_lshl_add_u64 v[106:107], v[106:107], 0, v[224:225]
	v_lshl_add_u64 v[250:251], v[106:107], 0, v[244:245]
	global_load_dwordx4 v[214:217], v[250:251], off
	v_lshl_add_u64 v[250:251], v[106:107], 0, v[244:245]
	global_load_dwordx4 v[218:221], v[250:251], off offset:256
	v_add_co_u32_e32 v110, vcc, s45, v106
	s_mov_b32 s45, 0x10000
	s_nop 0
	v_addc_co_u32_e32 v111, vcc, 0, v107, vcc
	v_add_co_u32_e32 v130, vcc, s45, v106
	s_mov_b32 s45, 0x18000
	s_nop 0
	v_addc_co_u32_e32 v131, vcc, 0, v107, vcc
	v_add_co_u32_e32 v134, vcc, s45, v106
	s_mov_b64 s[50:51], 0x8000
	s_nop 0
	v_addc_co_u32_e32 v135, vcc, 0, v107, vcc
	s_mov_b32 s45, 0x40000
	v_lshl_add_u64 v[108:109], v[106:107], 0, s[50:51]
	s_mov_b64 s[50:51], 0x10000
	v_add_co_u32_e32 v146, vcc, s45, v106
	v_lshl_add_u64 v[112:113], v[106:107], 0, s[50:51]
	s_mov_b64 s[50:51], 0x18000
	v_addc_co_u32_e32 v147, vcc, 0, v107, vcc
	s_mov_b32 s45, 0x48000
	v_lshl_add_u64 v[132:133], v[106:107], 0, s[50:51]
	s_mov_b64 s[50:51], 0x40000
	v_add_co_u32_e32 v150, vcc, s45, v106
	v_lshl_add_u64 v[136:137], v[106:107], 0, s[50:51]
	s_mov_b64 s[50:51], 0x48000
	v_addc_co_u32_e32 v151, vcc, 0, v107, vcc
	s_mov_b32 s45, 0x50000
	v_lshl_add_u64 v[148:149], v[106:107], 0, s[50:51]
	s_mov_b64 s[50:51], 0x50000
	v_add_co_u32_e32 v228, vcc, s45, v106
	v_lshl_add_u64 v[226:227], v[106:107], 0, s[50:51]
	s_nop 0
	v_addc_co_u32_e32 v229, vcc, 0, v107, vcc
	s_mov_b64 s[50:51], 0x58000
	s_mov_b32 s45, 0x58000
	v_lshl_add_u64 v[236:237], v[106:107], 0, s[50:51]
	v_add_co_u32_e32 v106, vcc, s45, v106
	s_lshl_b32 s50, s70, 2
	s_nop 0
	v_addc_co_u32_e32 v107, vcc, 0, v107, vcc
	v_lshl_add_u64 v[250:251], v[110:111], 0, v[244:245]
	global_load_dwordx4 v[182:185], v[250:251], off
	v_lshl_add_u64 v[250:251], v[108:109], 0, v[244:245]
	global_load_dwordx4 v[178:181], v[250:251], off offset:256
	v_lshl_add_u64 v[250:251], v[130:131], 0, v[244:245]
	global_load_dwordx4 v[174:177], v[250:251], off
	v_lshl_add_u64 v[250:251], v[112:113], 0, v[244:245]
	global_load_dwordx4 v[170:173], v[250:251], off offset:256
	v_lshl_add_u64 v[250:251], v[134:135], 0, v[244:245]
	global_load_dwordx4 v[166:169], v[250:251], off
	v_lshl_add_u64 v[250:251], v[132:133], 0, v[244:245]
	global_load_dwordx4 v[162:165], v[250:251], off offset:256
	v_lshl_add_u64 v[250:251], v[146:147], 0, v[244:245]
	global_load_dwordx4 v[158:161], v[250:251], off
	v_lshl_add_u64 v[250:251], v[136:137], 0, v[244:245]
	global_load_dwordx4 v[154:157], v[250:251], off offset:256
	s_nop 0
	v_lshl_add_u64 v[250:251], v[150:151], 0, v[244:245]
	global_load_dwordx4 v[150:153], v[250:251], off
	s_nop 0
	v_lshl_add_u64 v[250:251], v[148:149], 0, v[244:245]
	global_load_dwordx4 v[146:149], v[250:251], off offset:256
	s_nop 0
	v_lshl_add_u64 v[250:251], v[228:229], 0, v[244:245]
	global_load_dwordx4 v[134:137], v[250:251], off
	v_lshl_add_u64 v[250:251], v[226:227], 0, v[244:245]
	global_load_dwordx4 v[130:133], v[250:251], off offset:256
	v_lshl_add_u64 v[250:251], v[106:107], 0, v[244:245]
	global_load_dwordx4 v[110:113], v[250:251], off
	s_nop 0
	v_lshl_add_u64 v[250:251], v[236:237], 0, v[244:245]
	global_load_dwordx4 v[106:109], v[250:251], off offset:256
	v_cmp_eq_u32_e32 vcc, 0, v213
	s_ashr_i32 s51, s50, 31
	s_waitcnt vmcnt(0)
	ds_bpermute_b32 v214, v246, v214
	ds_bpermute_b32 v215, v246, v215
	ds_bpermute_b32 v216, v246, v216
	ds_bpermute_b32 v217, v246, v217
	ds_bpermute_b32 v218, v246, v218
	ds_bpermute_b32 v219, v246, v219
	ds_bpermute_b32 v220, v246, v220
	ds_bpermute_b32 v221, v246, v221
	ds_bpermute_b32 v182, v246, v182
	ds_bpermute_b32 v183, v246, v183
	ds_bpermute_b32 v184, v246, v184
	ds_bpermute_b32 v185, v246, v185
	ds_bpermute_b32 v178, v246, v178
	ds_bpermute_b32 v179, v246, v179
	ds_bpermute_b32 v180, v246, v180
	ds_bpermute_b32 v181, v246, v181
	ds_bpermute_b32 v174, v246, v174
	ds_bpermute_b32 v175, v246, v175
	ds_bpermute_b32 v176, v246, v176
	ds_bpermute_b32 v177, v246, v177
	ds_bpermute_b32 v170, v246, v170
	ds_bpermute_b32 v171, v246, v171
	ds_bpermute_b32 v172, v246, v172
	ds_bpermute_b32 v173, v246, v173
	ds_bpermute_b32 v166, v246, v166
	ds_bpermute_b32 v167, v246, v167
	ds_bpermute_b32 v168, v246, v168
	ds_bpermute_b32 v169, v246, v169
	ds_bpermute_b32 v162, v246, v162
	ds_bpermute_b32 v163, v246, v163
	ds_bpermute_b32 v164, v246, v164
	ds_bpermute_b32 v165, v246, v165
	ds_bpermute_b32 v158, v246, v158
	ds_bpermute_b32 v159, v246, v159
	ds_bpermute_b32 v160, v246, v160
	ds_bpermute_b32 v161, v246, v161
	ds_bpermute_b32 v154, v246, v154
	ds_bpermute_b32 v155, v246, v155
	ds_bpermute_b32 v156, v246, v156
	ds_bpermute_b32 v157, v246, v157
	ds_bpermute_b32 v150, v246, v150
	ds_bpermute_b32 v151, v246, v151
	ds_bpermute_b32 v152, v246, v152
	ds_bpermute_b32 v153, v246, v153
	ds_bpermute_b32 v146, v246, v146
	ds_bpermute_b32 v147, v246, v147
	ds_bpermute_b32 v148, v246, v148
	ds_bpermute_b32 v149, v246, v149
	ds_bpermute_b32 v134, v246, v134
	ds_bpermute_b32 v135, v246, v135
	ds_bpermute_b32 v136, v246, v136
	ds_bpermute_b32 v137, v246, v137
	ds_bpermute_b32 v130, v246, v130
	ds_bpermute_b32 v131, v246, v131
	ds_bpermute_b32 v132, v246, v132
	ds_bpermute_b32 v133, v246, v133
	ds_bpermute_b32 v110, v246, v110
	ds_bpermute_b32 v111, v246, v111
	ds_bpermute_b32 v112, v246, v112
	ds_bpermute_b32 v113, v246, v113
	ds_bpermute_b32 v106, v246, v106
	ds_bpermute_b32 v107, v246, v107
	ds_bpermute_b32 v108, v246, v108
	ds_bpermute_b32 v109, v246, v109
	s_waitcnt lgkmcnt(0)
; __device__ __forceinline__ unsigned cvt_pk_bf16(float lo, float hi) { unsigned r; asm volatile("v_cvt_pk_bf16_f32 %0, %1, %2" : "=v"(r) : "v"(lo), "v"(hi)); return r; }
;     __device__ __forceinline__ void finish_half(const f32x4 (&acc)[2][2][4][2], const f32x4 (&r)[4][2][2], const Unit& u, int ai, int rl0, int col0, int wc, int fq) const {
;     ...
;         for (int m = 0; m < 4; ++m) { const size_t row = (size_t)(u.pm * BM + rl0 + ai * HALF + m * 16); const size_t off = row * 1024 + col0; float q = 0.f;
; #pragma unroll
;             for (int bj = 0; bj < 2; ++bj) {
;                 const f32x4 v0 = acc[ai][bj][m][0] + r[m][bj][0], v1 = acc[ai][bj][m][1] + r[m][bj][1];
;                 if (out32) { *(f32x4*)(out32 + off + bj * HALF) = v0; *(f32x4*)(out32 + off + bj * HALF + 4) = v1; }
;                 q += (v0[0] * v0[0] + v0[1] * v0[1]) + (v0[2] * v0[2] + v0[3] * v0[3]) + (v1[0] * v1[0] + v1[1] * v1[1]) + (v1[2] * v1[2] + v1[3] * v1[3]);
;                 u32x4 w; w.x = cvt_pk_bf16(v0[0], v0[1]); w.y = cvt_pk_bf16(v0[2], v0[3]); w.z = cvt_pk_bf16(v1[0], v1[1]); w.w = cvt_pk_bf16(v1[2], v1[3]);
;                 *(u32x4*)(hb + off + bj * HALF) = w; }
;             q += __shfl_xor(q, 16); q += __shfl_xor(q, 32);
;             if (fq == 0) ssq[row * 16 + u.pn * 4 + wc] = q; }
;     __device__ __forceinline__ void operator()(const f32x4 (&acc)[2][2][4][2], const Unit& u, int wr, int wc, int fr, int fq) const {
;     ...
;                     for (int bj = 0; bj < 2; ++bj) { const u32x4 t = hv[ai][m][bj];
;                         r[m][bj][0] = (f32x4){__uint_as_float(t.x << 16), __uint_as_float(t.x & 0xffff0000u), __uint_as_float(t.y << 16), __uint_as_float(t.y & 0xffff0000u)};
;                         r[m][bj][1] = (f32x4){__uint_as_float(t.z << 16), __uint_as_float(t.z & 0xffff0000u), __uint_as_float(t.w << 16), __uint_as_float(t.w & 0xffff0000u)}; }
	v_lshlrev_b32_e32 v226, 16, v214
	v_and_b32_e32 v227, 0xffff0000, v214
	v_lshlrev_b32_e32 v214, 16, v215
	v_and_b32_e32 v215, 0xffff0000, v215
	v_lshlrev_b32_e32 v228, 16, v216
	v_and_b32_e32 v229, 0xffff0000, v216
	v_lshlrev_b32_e32 v216, 16, v217
	v_and_b32_e32 v217, 0xffff0000, v217
	v_pk_add_f32 v[144:145], v[144:145], v[214:215]
	v_pk_add_f32 v[142:143], v[142:143], v[226:227]
	v_pk_add_f32 v[214:215], v[140:141], v[216:217]
	v_pk_add_f32 v[140:141], v[138:139], v[228:229]
	v_mul_f32_e32 v138, v143, v143
	v_mul_f32_e32 v139, v145, v145
	v_fmac_f32_e32 v138, v142, v142
	v_fmac_f32_e32 v139, v144, v144
	v_add_f32_e32 v138, v138, v139
	v_mul_f32_e32 v139, v141, v141
	v_fmac_f32_e32 v139, v140, v140
	v_lshlrev_b32_e32 v236, 16, v218
	v_and_b32_e32 v237, 0xffff0000, v218
	v_lshlrev_b32_e32 v218, 16, v219
	v_and_b32_e32 v219, 0xffff0000, v219
	v_add_f32_e32 v138, v139, v138
	v_mul_f32_e32 v139, v215, v215
	v_lshlrev_b32_e32 v238, 16, v220
	v_and_b32_e32 v239, 0xffff0000, v220
	v_fmac_f32_e32 v139, v214, v214
	v_pk_add_f32 v[128:129], v[128:129], v[218:219]
	v_pk_add_f32 v[126:127], v[126:127], v[236:237]
	v_add_f32_e32 v213, v139, v138
	v_cvt_pk_bf16_f32 v138, v142, v143
	v_cvt_pk_bf16_f32 v139, v144, v145
	v_pk_add_f32 v[144:145], v[122:123], v[238:239]
	v_mul_f32_e32 v122, v127, v127
	v_mul_f32_e32 v123, v129, v129
	v_fmac_f32_e32 v122, v126, v126
	v_fmac_f32_e32 v123, v128, v128
	v_lshlrev_b32_e32 v220, 16, v221
	v_and_b32_e32 v221, 0xffff0000, v221
	v_add_f32_e32 v122, v122, v123
	v_mul_f32_e32 v123, v145, v145
	v_pk_add_f32 v[142:143], v[124:125], v[220:221]
	v_fmac_f32_e32 v123, v144, v144
	v_add_f32_e32 v122, v123, v122
	v_mul_f32_e32 v123, v143, v143
	v_fmac_f32_e32 v123, v142, v142
	v_add_f32_e32 v122, v123, v122
	v_add_f32_e32 v125, v213, v122
	v_mov_b32_e32 v213, v125
	v_mov_b32_e32 v247, v125
	s_nop 1
	v_permlane16_swap_b32_e32 v247, v213
	v_lshl_add_u64 v[122:123], s[28:29], 0, v[224:225]
	v_cvt_pk_bf16_f32 v140, v140, v141
	v_cvt_pk_bf16_f32 v141, v214, v215
	v_lshl_add_u64 v[214:215], v[122:123], 0, v[222:223]
	s_waitcnt lgkmcnt(0)
	v_add_f32_e32 v122, v125, v213
	v_mov_b32_e32 v123, v122
	v_mov_b32_e32 v247, v122
	s_nop 1
	v_permlane32_swap_b32_e32 v247, v123
	global_store_dwordx4 v[214:215], v[138:141], off
	v_cvt_pk_bf16_f32 v124, v126, v127
	v_cvt_pk_bf16_f32 v125, v128, v129
	v_cvt_pk_bf16_f32 v126, v144, v145
	v_cvt_pk_bf16_f32 v127, v142, v143
	global_store_dwordx4 v[214:215], v[124:127], off offset:256
	s_and_saveexec_b64 s[52:53], vcc
	s_cbranch_execz .LBB0_572
	v_lshlrev_b64 v[124:125], 6, v[208:209]
	v_lshl_add_u64 v[124:125], s[36:37], 0, v[124:125]
	v_lshl_add_u64 v[124:125], s[50:51], 2, v[124:125]
	s_lshl_b32 s70, s65, 2
	v_lshl_add_u64 v[124:125], v[124:125], 0, s[70:71]
	s_waitcnt lgkmcnt(0)
	v_add_f32_e32 v122, v122, v123
	global_store_dword v[124:125], v122, off
.LBB0_572:
	s_or_b64 exec, exec, s[52:53]
	v_lshlrev_b32_e32 v124, 16, v182
	v_and_b32_e32 v125, 0xffff0000, v182
	v_lshlrev_b32_e32 v126, 16, v183
	v_and_b32_e32 v127, 0xffff0000, v183
	v_lshlrev_b32_e32 v128, 16, v184
	v_and_b32_e32 v129, 0xffff0000, v184
	v_lshlrev_b32_e32 v138, 16, v185
	v_and_b32_e32 v139, 0xffff0000, v185
	v_pk_add_f32 v[120:121], v[120:121], v[126:127]
	v_pk_add_f32 v[118:119], v[118:119], v[124:125]
	v_pk_add_f32 v[124:125], v[116:117], v[138:139]
	v_pk_add_f32 v[116:117], v[114:115], v[128:129]
	v_mul_f32_e32 v114, v119, v119
	v_mul_f32_e32 v115, v121, v121
	v_fmac_f32_e32 v114, v118, v118
	v_fmac_f32_e32 v115, v120, v120
	v_add_f32_e32 v114, v114, v115
	v_mul_f32_e32 v115, v117, v117
	v_fmac_f32_e32 v115, v116, v116
	v_lshlrev_b32_e32 v140, 16, v178
	v_and_b32_e32 v141, 0xffff0000, v178
	v_lshlrev_b32_e32 v142, 16, v179
	v_and_b32_e32 v143, 0xffff0000, v179
	v_add_f32_e32 v114, v115, v114
	v_mul_f32_e32 v115, v125, v125
	v_lshlrev_b32_e32 v144, 16, v180
	v_and_b32_e32 v145, 0xffff0000, v180
	v_fmac_f32_e32 v115, v124, v124
	v_pk_add_f32 v[104:105], v[104:105], v[142:143]
	v_pk_add_f32 v[102:103], v[102:103], v[140:141]
	v_add_f32_e32 v126, v115, v114
	v_cvt_pk_bf16_f32 v114, v118, v119
	v_cvt_pk_bf16_f32 v115, v120, v121
	v_cvt_pk_bf16_f32 v116, v116, v117
	v_cvt_pk_bf16_f32 v117, v124, v125
	v_pk_add_f32 v[124:125], v[98:99], v[144:145]
	v_mul_f32_e32 v98, v103, v103
	v_mul_f32_e32 v99, v105, v105
	v_fmac_f32_e32 v98, v102, v102
	v_fmac_f32_e32 v99, v104, v104
	v_lshlrev_b32_e32 v178, 16, v181
	v_and_b32_e32 v179, 0xffff0000, v181
	v_add_f32_e32 v98, v98, v99
	v_mul_f32_e32 v99, v125, v125
	v_pk_add_f32 v[120:121], v[100:101], v[178:179]
	v_fmac_f32_e32 v99, v124, v124
	v_add_f32_e32 v98, v99, v98
	v_mul_f32_e32 v99, v121, v121
	v_fmac_f32_e32 v99, v120, v120
	v_add_f32_e32 v98, v99, v98
	v_add_f32_e32 v101, v126, v98
	s_or_b32 s45, s43, 16
	v_mov_b32_e32 v126, v101
	v_mov_b32_e32 v247, v101
	s_nop 1
	v_permlane16_swap_b32_e32 v247, v126
	v_add_u32_e32 v122, s45, v212
	s_waitcnt lgkmcnt(1)
	v_ashrrev_i32_e32 v123, 31, v122
	v_lshlrev_b64 v[118:119], 11, v[122:123]
	v_lshl_add_u64 v[98:99], s[28:29], 0, v[118:119]
	v_lshl_add_u64 v[118:119], v[206:207], 1, v[98:99]
	s_waitcnt lgkmcnt(0)
	v_add_f32_e32 v98, v101, v126
	v_mov_b32_e32 v99, v98
	v_mov_b32_e32 v247, v98
	s_nop 1
	v_permlane32_swap_b32_e32 v247, v99
	global_store_dwordx4 v[118:119], v[114:117], off
	v_cvt_pk_bf16_f32 v100, v102, v103
	v_cvt_pk_bf16_f32 v101, v104, v105
	v_cvt_pk_bf16_f32 v102, v124, v125
	v_cvt_pk_bf16_f32 v103, v120, v121
	global_store_dwordx4 v[118:119], v[100:103], off offset:256
	s_and_saveexec_b64 s[52:53], vcc
	s_cbranch_execz .LBB0_574
	v_lshlrev_b64 v[100:101], 6, v[122:123]
	v_lshl_add_u64 v[100:101], s[36:37], 0, v[100:101]
	v_lshl_add_u64 v[100:101], s[50:51], 2, v[100:101]
	s_lshl_b32 s70, s65, 2
	v_lshl_add_u64 v[100:101], v[100:101], 0, s[70:71]
	s_waitcnt lgkmcnt(0)
	v_add_f32_e32 v98, v98, v99
	global_store_dword v[100:101], v98, off
; __device__ __forceinline__ unsigned cvt_pk_bf16(float lo, float hi) { unsigned r; asm volatile("v_cvt_pk_bf16_f32 %0, %1, %2" : "=v"(r) : "v"(lo), "v"(hi)); return r; }
;     __device__ __forceinline__ void finish_half(const f32x4 (&acc)[2][2][4][2], const f32x4 (&r)[4][2][2], const Unit& u, int ai, int rl0, int col0, int wc, int fq) const {
;     ...
;         for (int m = 0; m < 4; ++m) { const size_t row = (size_t)(u.pm * BM + rl0 + ai * HALF + m * 16); const size_t off = row * 1024 + col0; float q = 0.f;
; #pragma unroll
;             for (int bj = 0; bj < 2; ++bj) {
;                 const f32x4 v0 = acc[ai][bj][m][0] + r[m][bj][0], v1 = acc[ai][bj][m][1] + r[m][bj][1];
;                 if (out32) { *(f32x4*)(out32 + off + bj * HALF) = v0; *(f32x4*)(out32 + off + bj * HALF + 4) = v1; }
;                 q += (v0[0] * v0[0] + v0[1] * v0[1]) + (v0[2] * v0[2] + v0[3] * v0[3]) + (v1[0] * v1[0] + v1[1] * v1[1]) + (v1[2] * v1[2] + v1[3] * v1[3]);
;                 u32x4 w; w.x = cvt_pk_bf16(v0[0], v0[1]); w.y = cvt_pk_bf16(v0[2], v0[3]); w.z = cvt_pk_bf16(v1[0], v1[1]); w.w = cvt_pk_bf16(v1[2], v1[3]);
;                 *(u32x4*)(hb + off + bj * HALF) = w; }
;             q += __shfl_xor(q, 16); q += __shfl_xor(q, 32);
;             if (fq == 0) ssq[row * 16 + u.pn * 4 + wc] = q; }
;     __device__ __forceinline__ void operator()(const f32x4 (&acc)[2][2][4][2], const Unit& u, int wr, int wc, int fr, int fq) const {
;     ...
;                     for (int bj = 0; bj < 2; ++bj) { const u32x4 t = hv[ai][m][bj];
;                         r[m][bj][0] = (f32x4){__uint_as_float(t.x << 16), __uint_as_float(t.x & 0xffff0000u), __uint_as_float(t.y << 16), __uint_as_float(t.y & 0xffff0000u)};
;                         r[m][bj][1] = (f32x4){__uint_as_float(t.z << 16), __uint_as_float(t.z & 0xffff0000u), __uint_as_float(t.w << 16), __uint_as_float(t.w & 0xffff0000u)}; }
.LBB0_574:
	s_or_b64 exec, exec, s[52:53]
	v_lshlrev_b32_e32 v100, 16, v174
	v_and_b32_e32 v101, 0xffff0000, v174
	v_lshlrev_b32_e32 v102, 16, v175
	v_and_b32_e32 v103, 0xffff0000, v175
	v_lshlrev_b32_e32 v104, 16, v176
	v_and_b32_e32 v105, 0xffff0000, v176
	v_lshlrev_b32_e32 v114, 16, v177
	v_and_b32_e32 v115, 0xffff0000, v177
	v_pk_add_f32 v[96:97], v[96:97], v[102:103]
	v_pk_add_f32 v[94:95], v[94:95], v[100:101]
	v_pk_add_f32 v[100:101], v[92:93], v[114:115]
	v_pk_add_f32 v[92:93], v[90:91], v[104:105]
	v_mul_f32_e32 v90, v95, v95
	v_mul_f32_e32 v91, v97, v97
	v_fmac_f32_e32 v90, v94, v94
	v_fmac_f32_e32 v91, v96, v96
	v_add_f32_e32 v90, v90, v91
	v_mul_f32_e32 v91, v93, v93
	v_fmac_f32_e32 v91, v92, v92
	v_lshlrev_b32_e32 v116, 16, v170
	v_and_b32_e32 v117, 0xffff0000, v170
	v_lshlrev_b32_e32 v118, 16, v171
	v_and_b32_e32 v119, 0xffff0000, v171
	v_add_f32_e32 v90, v91, v90
	v_mul_f32_e32 v91, v101, v101
	v_lshlrev_b32_e32 v120, 16, v172
	v_and_b32_e32 v121, 0xffff0000, v172
	v_fmac_f32_e32 v91, v100, v100
	v_pk_add_f32 v[88:89], v[88:89], v[118:119]
	v_pk_add_f32 v[86:87], v[86:87], v[116:117]
	v_add_f32_e32 v102, v91, v90
	v_cvt_pk_bf16_f32 v90, v94, v95
	v_cvt_pk_bf16_f32 v91, v96, v97
	v_cvt_pk_bf16_f32 v92, v92, v93
	v_cvt_pk_bf16_f32 v93, v100, v101
	v_pk_add_f32 v[100:101], v[82:83], v[120:121]
	v_mul_f32_e32 v82, v87, v87
	v_mul_f32_e32 v83, v89, v89
	v_fmac_f32_e32 v82, v86, v86
	v_fmac_f32_e32 v83, v88, v88
	v_lshlrev_b32_e32 v122, 16, v173
	v_and_b32_e32 v123, 0xffff0000, v173
	v_add_f32_e32 v82, v82, v83
	v_mul_f32_e32 v83, v101, v101
	v_pk_add_f32 v[96:97], v[84:85], v[122:123]
	v_fmac_f32_e32 v83, v100, v100
	v_add_f32_e32 v82, v83, v82
	v_mul_f32_e32 v83, v97, v97
	v_fmac_f32_e32 v83, v96, v96
	v_add_f32_e32 v82, v83, v82
	v_add_f32_e32 v85, v102, v82
	s_or_b32 s54, s43, 32
	v_mov_b32_e32 v102, v85
	v_mov_b32_e32 v247, v85
	s_nop 1
	v_permlane16_swap_b32_e32 v247, v102
	v_add_u32_e32 v98, s54, v212
	s_waitcnt lgkmcnt(1)
	v_ashrrev_i32_e32 v99, 31, v98
	v_lshlrev_b64 v[94:95], 11, v[98:99]
	v_lshl_add_u64 v[82:83], s[28:29], 0, v[94:95]
	v_lshl_add_u64 v[94:95], v[206:207], 1, v[82:83]
	s_waitcnt lgkmcnt(0)
	v_add_f32_e32 v82, v85, v102
	v_mov_b32_e32 v83, v82
	v_mov_b32_e32 v247, v82
	s_nop 1
	v_permlane32_swap_b32_e32 v247, v83
	global_store_dwordx4 v[94:95], v[90:93], off
	v_cvt_pk_bf16_f32 v84, v86, v87
	v_cvt_pk_bf16_f32 v85, v88, v89
	v_cvt_pk_bf16_f32 v86, v100, v101
	v_cvt_pk_bf16_f32 v87, v96, v97
	global_store_dwordx4 v[94:95], v[84:87], off offset:256
	s_and_saveexec_b64 s[52:53], vcc
	s_cbranch_execz .LBB0_576
	v_lshlrev_b64 v[84:85], 6, v[98:99]
	v_lshl_add_u64 v[84:85], s[36:37], 0, v[84:85]
	v_lshl_add_u64 v[84:85], s[50:51], 2, v[84:85]
	s_lshl_b32 s70, s65, 2
	v_lshl_add_u64 v[84:85], v[84:85], 0, s[70:71]
	s_waitcnt lgkmcnt(0)
	v_add_f32_e32 v82, v82, v83
	global_store_dword v[84:85], v82, off
.LBB0_576:
	s_or_b64 exec, exec, s[52:53]
	v_lshlrev_b32_e32 v84, 16, v166
	v_and_b32_e32 v85, 0xffff0000, v166
	v_lshlrev_b32_e32 v86, 16, v167
	v_and_b32_e32 v87, 0xffff0000, v167
	v_lshlrev_b32_e32 v88, 16, v168
	v_and_b32_e32 v89, 0xffff0000, v168
	v_lshlrev_b32_e32 v90, 16, v169
	v_and_b32_e32 v91, 0xffff0000, v169
	v_pk_add_f32 v[80:81], v[80:81], v[86:87]
	v_pk_add_f32 v[78:79], v[78:79], v[84:85]
	v_pk_add_f32 v[84:85], v[76:77], v[90:91]
	v_pk_add_f32 v[76:77], v[74:75], v[88:89]
	v_mul_f32_e32 v74, v79, v79
	v_mul_f32_e32 v75, v81, v81
	v_fmac_f32_e32 v74, v78, v78
	v_fmac_f32_e32 v75, v80, v80
	v_add_f32_e32 v74, v74, v75
	v_mul_f32_e32 v75, v77, v77
	v_fmac_f32_e32 v75, v76, v76
	v_lshlrev_b32_e32 v92, 16, v162
	v_and_b32_e32 v93, 0xffff0000, v162
	v_lshlrev_b32_e32 v94, 16, v163
	v_and_b32_e32 v95, 0xffff0000, v163
	v_add_f32_e32 v74, v75, v74
	v_mul_f32_e32 v75, v85, v85
	v_lshlrev_b32_e32 v96, 16, v164
	v_and_b32_e32 v97, 0xffff0000, v164
	v_fmac_f32_e32 v75, v84, v84
	v_pk_add_f32 v[72:73], v[72:73], v[94:95]
	v_pk_add_f32 v[70:71], v[70:71], v[92:93]
	v_add_f32_e32 v86, v75, v74
	v_cvt_pk_bf16_f32 v74, v78, v79
	v_cvt_pk_bf16_f32 v75, v80, v81
	v_cvt_pk_bf16_f32 v76, v76, v77
	v_cvt_pk_bf16_f32 v77, v84, v85
	v_pk_add_f32 v[84:85], v[66:67], v[96:97]
	v_mul_f32_e32 v66, v71, v71
	v_mul_f32_e32 v67, v73, v73
	v_fmac_f32_e32 v66, v70, v70
	v_fmac_f32_e32 v67, v72, v72
	v_lshlrev_b32_e32 v98, 16, v165
	v_and_b32_e32 v99, 0xffff0000, v165
	v_add_f32_e32 v66, v66, v67
	v_mul_f32_e32 v67, v85, v85
	v_pk_add_f32 v[80:81], v[68:69], v[98:99]
	v_fmac_f32_e32 v67, v84, v84
	v_add_f32_e32 v66, v67, v66
	v_mul_f32_e32 v67, v81, v81
	v_fmac_f32_e32 v67, v80, v80
	v_add_f32_e32 v66, v67, v66
	v_add_f32_e32 v69, v86, v66
	s_or_b32 s55, s43, 48
	v_mov_b32_e32 v86, v69
	v_mov_b32_e32 v247, v69
	s_nop 1
	v_permlane16_swap_b32_e32 v247, v86
	v_add_u32_e32 v82, s55, v212
	s_waitcnt lgkmcnt(1)
	v_ashrrev_i32_e32 v83, 31, v82
	v_lshlrev_b64 v[78:79], 11, v[82:83]
	v_lshl_add_u64 v[66:67], s[28:29], 0, v[78:79]
	v_lshl_add_u64 v[78:79], v[206:207], 1, v[66:67]
	s_waitcnt lgkmcnt(0)
	v_add_f32_e32 v66, v69, v86
	v_mov_b32_e32 v67, v66
	v_mov_b32_e32 v247, v66
	s_nop 1
	v_permlane32_swap_b32_e32 v247, v67
	global_store_dwordx4 v[78:79], v[74:77], off
	v_cvt_pk_bf16_f32 v68, v70, v71
	v_cvt_pk_bf16_f32 v69, v72, v73
	v_cvt_pk_bf16_f32 v70, v84, v85
	v_cvt_pk_bf16_f32 v71, v80, v81
	global_store_dwordx4 v[78:79], v[68:71], off offset:256
	s_and_saveexec_b64 s[52:53], vcc
	s_cbranch_execz .LBB0_578
	v_lshlrev_b64 v[68:69], 6, v[82:83]
	v_lshl_add_u64 v[68:69], s[36:37], 0, v[68:69]
	v_lshl_add_u64 v[68:69], s[50:51], 2, v[68:69]
	s_lshl_b32 s70, s65, 2
	v_lshl_add_u64 v[68:69], v[68:69], 0, s[70:71]
	s_waitcnt lgkmcnt(0)
	v_add_f32_e32 v66, v66, v67
	global_store_dword v[68:69], v66, off
; __device__ __forceinline__ unsigned cvt_pk_bf16(float lo, float hi) { unsigned r; asm volatile("v_cvt_pk_bf16_f32 %0, %1, %2" : "=v"(r) : "v"(lo), "v"(hi)); return r; }
;     __device__ __forceinline__ void finish_half(const f32x4 (&acc)[2][2][4][2], const f32x4 (&r)[4][2][2], const Unit& u, int ai, int rl0, int col0, int wc, int fq) const {
;     ...
;         for (int m = 0; m < 4; ++m) { const size_t row = (size_t)(u.pm * BM + rl0 + ai * HALF + m * 16); const size_t off = row * 1024 + col0; float q = 0.f;
; #pragma unroll
;             for (int bj = 0; bj < 2; ++bj) {
;                 const f32x4 v0 = acc[ai][bj][m][0] + r[m][bj][0], v1 = acc[ai][bj][m][1] + r[m][bj][1];
;                 if (out32) { *(f32x4*)(out32 + off + bj * HALF) = v0; *(f32x4*)(out32 + off + bj * HALF + 4) = v1; }
;                 q += (v0[0] * v0[0] + v0[1] * v0[1]) + (v0[2] * v0[2] + v0[3] * v0[3]) + (v1[0] * v1[0] + v1[1] * v1[1]) + (v1[2] * v1[2] + v1[3] * v1[3]);
;                 u32x4 w; w.x = cvt_pk_bf16(v0[0], v0[1]); w.y = cvt_pk_bf16(v0[2], v0[3]); w.z = cvt_pk_bf16(v1[0], v1[1]); w.w = cvt_pk_bf16(v1[2], v1[3]);
;                 *(u32x4*)(hb + off + bj * HALF) = w; }
;             q += __shfl_xor(q, 16); q += __shfl_xor(q, 32);
;             if (fq == 0) ssq[row * 16 + u.pn * 4 + wc] = q; }
;     __device__ __forceinline__ void operator()(const f32x4 (&acc)[2][2][4][2], const Unit& u, int wr, int wc, int fr, int fq) const {
;     ...
;                     for (int bj = 0; bj < 2; ++bj) { const u32x4 t = hv[ai][m][bj];
;                         r[m][bj][0] = (f32x4){__uint_as_float(t.x << 16), __uint_as_float(t.x & 0xffff0000u), __uint_as_float(t.y << 16), __uint_as_float(t.y & 0xffff0000u)};
;                         r[m][bj][1] = (f32x4){__uint_as_float(t.z << 16), __uint_as_float(t.z & 0xffff0000u), __uint_as_float(t.w << 16), __uint_as_float(t.w & 0xffff0000u)}; }
.LBB0_578:
	s_or_b64 exec, exec, s[52:53]
	v_lshlrev_b32_e32 v70, 16, v158
	v_and_b32_e32 v71, 0xffff0000, v158
	v_lshlrev_b32_e32 v72, 16, v159
	v_and_b32_e32 v73, 0xffff0000, v159
	v_lshlrev_b32_e32 v74, 16, v160
	v_and_b32_e32 v75, 0xffff0000, v160
	v_lshlrev_b32_e32 v76, 16, v161
	v_and_b32_e32 v77, 0xffff0000, v161
	v_pk_add_f32 v[64:65], v[64:65], v[72:73]
	v_pk_add_f32 v[62:63], v[62:63], v[70:71]
	v_pk_add_f32 v[70:71], v[60:61], v[76:77]
	v_pk_add_f32 v[60:61], v[58:59], v[74:75]
	v_mul_f32_e32 v58, v63, v63
	v_mul_f32_e32 v59, v65, v65
	v_fmac_f32_e32 v58, v62, v62
	v_fmac_f32_e32 v59, v64, v64
	v_add_f32_e32 v58, v58, v59
	v_mul_f32_e32 v59, v61, v61
	v_fmac_f32_e32 v59, v60, v60
	v_lshlrev_b32_e32 v78, 16, v154
	v_and_b32_e32 v79, 0xffff0000, v154
	v_lshlrev_b32_e32 v80, 16, v155
	v_and_b32_e32 v81, 0xffff0000, v155
	v_add_f32_e32 v58, v59, v58
	v_mul_f32_e32 v59, v71, v71
	v_lshlrev_b32_e32 v82, 16, v156
	v_and_b32_e32 v83, 0xffff0000, v156
	v_fmac_f32_e32 v59, v70, v70
	v_pk_add_f32 v[56:57], v[56:57], v[80:81]
	v_pk_add_f32 v[54:55], v[54:55], v[78:79]
	v_add_f32_e32 v69, v59, v58
	v_cvt_pk_bf16_f32 v58, v62, v63
	v_cvt_pk_bf16_f32 v59, v64, v65
	v_cvt_pk_bf16_f32 v60, v60, v61
	v_cvt_pk_bf16_f32 v61, v70, v71
	v_pk_add_f32 v[70:71], v[50:51], v[82:83]
	v_mul_f32_e32 v50, v55, v55
	v_mul_f32_e32 v51, v57, v57
	v_fmac_f32_e32 v50, v54, v54
	v_fmac_f32_e32 v51, v56, v56
	v_lshlrev_b32_e32 v84, 16, v157
	v_and_b32_e32 v85, 0xffff0000, v157
	v_add_f32_e32 v50, v50, v51
	v_mul_f32_e32 v51, v71, v71
	v_pk_add_f32 v[64:65], v[52:53], v[84:85]
	v_fmac_f32_e32 v51, v70, v70
	v_add_f32_e32 v50, v51, v50
	v_mul_f32_e32 v51, v65, v65
	v_fmac_f32_e32 v51, v64, v64
	v_add_f32_e32 v50, v51, v50
	v_add_f32_e32 v53, v69, v50
	v_add_u32_e32 v68, 0x80, v212
	v_mov_b32_e32 v69, v53
	v_mov_b32_e32 v247, v53
	s_nop 1
	v_permlane16_swap_b32_e32 v247, v69
	v_add_u32_e32 v66, s43, v68
	s_waitcnt lgkmcnt(1)
	v_ashrrev_i32_e32 v67, 31, v66
	v_lshlrev_b64 v[62:63], 11, v[66:67]
	v_lshl_add_u64 v[50:51], s[28:29], 0, v[62:63]
	v_lshl_add_u64 v[62:63], v[206:207], 1, v[50:51]
	s_waitcnt lgkmcnt(0)
	v_add_f32_e32 v50, v53, v69
	v_mov_b32_e32 v51, v50
	v_mov_b32_e32 v247, v50
	s_nop 1
	v_permlane32_swap_b32_e32 v247, v51
	global_store_dwordx4 v[62:63], v[58:61], off
	v_cvt_pk_bf16_f32 v52, v54, v55
	v_cvt_pk_bf16_f32 v53, v56, v57
	v_cvt_pk_bf16_f32 v54, v70, v71
	v_cvt_pk_bf16_f32 v55, v64, v65
	global_store_dwordx4 v[62:63], v[52:55], off offset:256
	s_and_saveexec_b64 s[52:53], vcc
	s_cbranch_execz .LBB0_580
	v_lshlrev_b64 v[52:53], 6, v[66:67]
	v_lshl_add_u64 v[52:53], s[36:37], 0, v[52:53]
	v_lshl_add_u64 v[52:53], s[50:51], 2, v[52:53]
	s_lshl_b32 s70, s65, 2
	v_lshl_add_u64 v[52:53], v[52:53], 0, s[70:71]
	s_waitcnt lgkmcnt(0)
	v_add_f32_e32 v50, v50, v51
	global_store_dword v[52:53], v50, off
.LBB0_580:
	s_or_b64 exec, exec, s[52:53]
	v_lshlrev_b32_e32 v52, 16, v150
	v_and_b32_e32 v53, 0xffff0000, v150
	v_lshlrev_b32_e32 v54, 16, v151
	v_and_b32_e32 v55, 0xffff0000, v151
	v_lshlrev_b32_e32 v56, 16, v152
	v_and_b32_e32 v57, 0xffff0000, v152
	v_lshlrev_b32_e32 v58, 16, v153
	v_and_b32_e32 v59, 0xffff0000, v153
	v_pk_add_f32 v[48:49], v[48:49], v[54:55]
	v_pk_add_f32 v[46:47], v[46:47], v[52:53]
	v_pk_add_f32 v[52:53], v[44:45], v[58:59]
	v_pk_add_f32 v[44:45], v[42:43], v[56:57]
	v_mul_f32_e32 v42, v47, v47
	v_mul_f32_e32 v43, v49, v49
	v_fmac_f32_e32 v42, v46, v46
	v_fmac_f32_e32 v43, v48, v48
	v_add_f32_e32 v42, v42, v43
	v_mul_f32_e32 v43, v45, v45
	v_fmac_f32_e32 v43, v44, v44
	v_lshlrev_b32_e32 v60, 16, v146
	v_and_b32_e32 v61, 0xffff0000, v146
	v_lshlrev_b32_e32 v62, 16, v147
	v_and_b32_e32 v63, 0xffff0000, v147
	v_add_f32_e32 v42, v43, v42
	v_mul_f32_e32 v43, v53, v53
	v_lshlrev_b32_e32 v64, 16, v148
	v_and_b32_e32 v65, 0xffff0000, v148
	v_fmac_f32_e32 v43, v52, v52
	v_pk_add_f32 v[40:41], v[40:41], v[62:63]
	v_pk_add_f32 v[38:39], v[38:39], v[60:61]
	v_add_f32_e32 v54, v43, v42
	v_cvt_pk_bf16_f32 v42, v46, v47
	v_cvt_pk_bf16_f32 v43, v48, v49
	v_cvt_pk_bf16_f32 v44, v44, v45
	v_cvt_pk_bf16_f32 v45, v52, v53
	v_pk_add_f32 v[52:53], v[34:35], v[64:65]
	v_mul_f32_e32 v34, v39, v39
	v_mul_f32_e32 v35, v41, v41
	v_fmac_f32_e32 v34, v38, v38
	v_fmac_f32_e32 v35, v40, v40
	v_lshlrev_b32_e32 v66, 16, v149
	v_and_b32_e32 v67, 0xffff0000, v149
	v_add_f32_e32 v34, v34, v35
	v_mul_f32_e32 v35, v53, v53
	v_pk_add_f32 v[48:49], v[36:37], v[66:67]
	v_fmac_f32_e32 v35, v52, v52
	v_add_f32_e32 v34, v35, v34
	v_mul_f32_e32 v35, v49, v49
	v_fmac_f32_e32 v35, v48, v48
	v_add_f32_e32 v34, v35, v34
	v_add_f32_e32 v37, v54, v34
	v_mov_b32_e32 v54, v37
	v_mov_b32_e32 v247, v37
	s_nop 1
	v_permlane16_swap_b32_e32 v247, v54
	v_add_u32_e32 v50, s45, v68
	s_waitcnt lgkmcnt(1)
	v_ashrrev_i32_e32 v51, 31, v50
	v_lshlrev_b64 v[46:47], 11, v[50:51]
	v_lshl_add_u64 v[34:35], s[28:29], 0, v[46:47]
	v_lshl_add_u64 v[46:47], v[206:207], 1, v[34:35]
	s_waitcnt lgkmcnt(0)
	v_add_f32_e32 v34, v37, v54
	v_mov_b32_e32 v35, v34
	v_mov_b32_e32 v247, v34
	s_nop 1
	v_permlane32_swap_b32_e32 v247, v35
	global_store_dwordx4 v[46:47], v[42:45], off
	v_cvt_pk_bf16_f32 v36, v38, v39
	v_cvt_pk_bf16_f32 v37, v40, v41
	v_cvt_pk_bf16_f32 v38, v52, v53
	v_cvt_pk_bf16_f32 v39, v48, v49
	global_store_dwordx4 v[46:47], v[36:39], off offset:256
	s_and_saveexec_b64 s[52:53], vcc
	s_cbranch_execz .LBB0_582
	v_lshlrev_b64 v[36:37], 6, v[50:51]
	v_lshl_add_u64 v[36:37], s[36:37], 0, v[36:37]
	v_lshl_add_u64 v[36:37], s[50:51], 2, v[36:37]
	s_lshl_b32 s70, s65, 2
	v_lshl_add_u64 v[36:37], v[36:37], 0, s[70:71]
	s_waitcnt lgkmcnt(0)
	v_add_f32_e32 v34, v34, v35
	global_store_dword v[36:37], v34, off
; __device__ __forceinline__ unsigned cvt_pk_bf16(float lo, float hi) { unsigned r; asm volatile("v_cvt_pk_bf16_f32 %0, %1, %2" : "=v"(r) : "v"(lo), "v"(hi)); return r; }
;     __device__ __forceinline__ void finish_half(const f32x4 (&acc)[2][2][4][2], const f32x4 (&r)[4][2][2], const Unit& u, int ai, int rl0, int col0, int wc, int fq) const {
;     ...
;         for (int m = 0; m < 4; ++m) { const size_t row = (size_t)(u.pm * BM + rl0 + ai * HALF + m * 16); const size_t off = row * 1024 + col0; float q = 0.f;
; #pragma unroll
;             for (int bj = 0; bj < 2; ++bj) {
;                 const f32x4 v0 = acc[ai][bj][m][0] + r[m][bj][0], v1 = acc[ai][bj][m][1] + r[m][bj][1];
;                 if (out32) { *(f32x4*)(out32 + off + bj * HALF) = v0; *(f32x4*)(out32 + off + bj * HALF + 4) = v1; }
;                 q += (v0[0] * v0[0] + v0[1] * v0[1]) + (v0[2] * v0[2] + v0[3] * v0[3]) + (v1[0] * v1[0] + v1[1] * v1[1]) + (v1[2] * v1[2] + v1[3] * v1[3]);
;                 u32x4 w; w.x = cvt_pk_bf16(v0[0], v0[1]); w.y = cvt_pk_bf16(v0[2], v0[3]); w.z = cvt_pk_bf16(v1[0], v1[1]); w.w = cvt_pk_bf16(v1[2], v1[3]);
;                 *(u32x4*)(hb + off + bj * HALF) = w; }
;             q += __shfl_xor(q, 16); q += __shfl_xor(q, 32);
;             if (fq == 0) ssq[row * 16 + u.pn * 4 + wc] = q; }
;     __device__ __forceinline__ void operator()(const f32x4 (&acc)[2][2][4][2], const Unit& u, int wr, int wc, int fr, int fq) const {
;     ...
;                     for (int bj = 0; bj < 2; ++bj) { const u32x4 t = hv[ai][m][bj];
;                         r[m][bj][0] = (f32x4){__uint_as_float(t.x << 16), __uint_as_float(t.x & 0xffff0000u), __uint_as_float(t.y << 16), __uint_as_float(t.y & 0xffff0000u)};
;                         r[m][bj][1] = (f32x4){__uint_as_float(t.z << 16), __uint_as_float(t.z & 0xffff0000u), __uint_as_float(t.w << 16), __uint_as_float(t.w & 0xffff0000u)}; }
.LBB0_582:
	s_or_b64 exec, exec, s[52:53]
	v_lshlrev_b32_e32 v36, 16, v134
	v_and_b32_e32 v37, 0xffff0000, v134
	v_lshlrev_b32_e32 v38, 16, v135
	v_and_b32_e32 v39, 0xffff0000, v135
	v_lshlrev_b32_e32 v40, 16, v136
	v_and_b32_e32 v41, 0xffff0000, v136
	v_lshlrev_b32_e32 v42, 16, v137
	v_and_b32_e32 v43, 0xffff0000, v137
	v_pk_add_f32 v[32:33], v[32:33], v[38:39]
	v_pk_add_f32 v[30:31], v[30:31], v[36:37]
	v_pk_add_f32 v[36:37], v[28:29], v[42:43]
	v_pk_add_f32 v[28:29], v[26:27], v[40:41]
	v_mul_f32_e32 v26, v31, v31
	v_mul_f32_e32 v27, v33, v33
	v_fmac_f32_e32 v26, v30, v30
	v_fmac_f32_e32 v27, v32, v32
	v_add_f32_e32 v26, v26, v27
	v_mul_f32_e32 v27, v29, v29
	v_fmac_f32_e32 v27, v28, v28
	v_lshlrev_b32_e32 v44, 16, v130
	v_and_b32_e32 v45, 0xffff0000, v130
	v_lshlrev_b32_e32 v46, 16, v131
	v_and_b32_e32 v47, 0xffff0000, v131
	v_add_f32_e32 v26, v27, v26
	v_mul_f32_e32 v27, v37, v37
	v_lshlrev_b32_e32 v48, 16, v132
	v_and_b32_e32 v49, 0xffff0000, v132
	v_fmac_f32_e32 v27, v36, v36
	v_pk_add_f32 v[24:25], v[24:25], v[46:47]
	v_pk_add_f32 v[22:23], v[22:23], v[44:45]
	v_add_f32_e32 v38, v27, v26
	v_cvt_pk_bf16_f32 v26, v30, v31
	v_cvt_pk_bf16_f32 v27, v32, v33
	v_cvt_pk_bf16_f32 v28, v28, v29
	v_cvt_pk_bf16_f32 v29, v36, v37
	v_pk_add_f32 v[36:37], v[18:19], v[48:49]
	v_mul_f32_e32 v18, v23, v23
	v_mul_f32_e32 v19, v25, v25
	v_fmac_f32_e32 v18, v22, v22
	v_fmac_f32_e32 v19, v24, v24
	v_lshlrev_b32_e32 v50, 16, v133
	v_and_b32_e32 v51, 0xffff0000, v133
	v_add_f32_e32 v18, v18, v19
	v_mul_f32_e32 v19, v37, v37
	v_pk_add_f32 v[32:33], v[20:21], v[50:51]
	v_fmac_f32_e32 v19, v36, v36
	v_add_f32_e32 v18, v19, v18
	v_mul_f32_e32 v19, v33, v33
	v_fmac_f32_e32 v19, v32, v32
	v_add_f32_e32 v18, v19, v18
	v_add_f32_e32 v21, v38, v18
	v_mov_b32_e32 v38, v21
	v_mov_b32_e32 v247, v21
	s_nop 1
	v_permlane16_swap_b32_e32 v247, v38
	v_add_u32_e32 v34, s54, v68
	s_waitcnt lgkmcnt(1)
	v_ashrrev_i32_e32 v35, 31, v34
	v_lshlrev_b64 v[30:31], 11, v[34:35]
	v_lshl_add_u64 v[18:19], s[28:29], 0, v[30:31]
	v_lshl_add_u64 v[30:31], v[206:207], 1, v[18:19]
	s_waitcnt lgkmcnt(0)
	v_add_f32_e32 v18, v21, v38
	v_mov_b32_e32 v19, v18
	v_mov_b32_e32 v247, v18
	s_nop 1
	v_permlane32_swap_b32_e32 v247, v19
	global_store_dwordx4 v[30:31], v[26:29], off
	v_cvt_pk_bf16_f32 v20, v22, v23
	v_cvt_pk_bf16_f32 v21, v24, v25
	v_cvt_pk_bf16_f32 v22, v36, v37
	v_cvt_pk_bf16_f32 v23, v32, v33
	global_store_dwordx4 v[30:31], v[20:23], off offset:256
	s_and_saveexec_b64 s[52:53], vcc
	s_cbranch_execz .LBB0_584
	v_lshlrev_b64 v[20:21], 6, v[34:35]
	v_lshl_add_u64 v[20:21], s[36:37], 0, v[20:21]
	v_lshl_add_u64 v[20:21], s[50:51], 2, v[20:21]
	s_lshl_b32 s70, s65, 2
	v_lshl_add_u64 v[20:21], v[20:21], 0, s[70:71]
	s_waitcnt lgkmcnt(0)
	v_add_f32_e32 v18, v18, v19
	global_store_dword v[20:21], v18, off
.LBB0_584:
	s_or_b64 exec, exec, s[52:53]
	v_lshlrev_b32_e32 v20, 16, v110
	v_and_b32_e32 v21, 0xffff0000, v110
	v_lshlrev_b32_e32 v22, 16, v111
	v_and_b32_e32 v23, 0xffff0000, v111
	v_lshlrev_b32_e32 v24, 16, v112
	v_and_b32_e32 v25, 0xffff0000, v112
	v_lshlrev_b32_e32 v26, 16, v113
	v_and_b32_e32 v27, 0xffff0000, v113
	v_pk_add_f32 v[16:17], v[16:17], v[22:23]
	v_pk_add_f32 v[14:15], v[14:15], v[20:21]
	v_pk_add_f32 v[20:21], v[12:13], v[26:27]
	v_pk_add_f32 v[12:13], v[10:11], v[24:25]
	v_mul_f32_e32 v10, v15, v15
	v_mul_f32_e32 v11, v17, v17
	v_fmac_f32_e32 v10, v14, v14
	v_fmac_f32_e32 v11, v16, v16
	v_add_f32_e32 v10, v10, v11
	v_mul_f32_e32 v11, v13, v13
	v_fmac_f32_e32 v11, v12, v12
	v_lshlrev_b32_e32 v28, 16, v106
	v_and_b32_e32 v29, 0xffff0000, v106
	v_lshlrev_b32_e32 v30, 16, v107
	v_and_b32_e32 v31, 0xffff0000, v107
	v_add_f32_e32 v10, v11, v10
	v_mul_f32_e32 v11, v21, v21
	v_lshlrev_b32_e32 v32, 16, v108
	v_and_b32_e32 v33, 0xffff0000, v108
	v_fmac_f32_e32 v11, v20, v20
	v_pk_add_f32 v[8:9], v[8:9], v[30:31]
	v_pk_add_f32 v[6:7], v[6:7], v[28:29]
	v_add_f32_e32 v22, v11, v10
	v_cvt_pk_bf16_f32 v10, v14, v15
	v_cvt_pk_bf16_f32 v11, v16, v17
	v_cvt_pk_bf16_f32 v12, v12, v13
	v_cvt_pk_bf16_f32 v13, v20, v21
	v_pk_add_f32 v[20:21], v[2:3], v[32:33]
	v_mul_f32_e32 v2, v7, v7
	v_mul_f32_e32 v3, v9, v9
	v_fmac_f32_e32 v2, v6, v6
	v_fmac_f32_e32 v3, v8, v8
	v_lshlrev_b32_e32 v34, 16, v109
	v_and_b32_e32 v35, 0xffff0000, v109
	v_add_f32_e32 v2, v2, v3
	v_mul_f32_e32 v3, v21, v21
	v_pk_add_f32 v[16:17], v[4:5], v[34:35]
	v_fmac_f32_e32 v3, v20, v20
	v_add_f32_e32 v2, v3, v2
	v_mul_f32_e32 v3, v17, v17
	v_fmac_f32_e32 v3, v16, v16
	v_add_f32_e32 v2, v3, v2
	v_add_f32_e32 v5, v22, v2
	v_mov_b32_e32 v22, v5
	v_mov_b32_e32 v247, v5
	s_nop 1
	v_permlane16_swap_b32_e32 v247, v22
	v_add_u32_e32 v18, s55, v68
	s_waitcnt lgkmcnt(1)
	v_ashrrev_i32_e32 v19, 31, v18
	v_lshlrev_b64 v[14:15], 11, v[18:19]
	v_lshl_add_u64 v[2:3], s[28:29], 0, v[14:15]
	v_lshl_add_u64 v[14:15], v[206:207], 1, v[2:3]
	s_waitcnt lgkmcnt(0)
	v_add_f32_e32 v2, v5, v22
	v_mov_b32_e32 v3, v2
	v_mov_b32_e32 v247, v2
	s_nop 1
	v_permlane32_swap_b32_e32 v247, v3
	global_store_dwordx4 v[14:15], v[10:13], off
	v_cvt_pk_bf16_f32 v4, v6, v7
	v_cvt_pk_bf16_f32 v5, v8, v9
	v_cvt_pk_bf16_f32 v6, v20, v21
	v_cvt_pk_bf16_f32 v7, v16, v17
	global_store_dwordx4 v[14:15], v[4:7], off offset:256
	s_and_saveexec_b64 s[52:53], vcc
	s_cbranch_execz .LBB0_586
	s_waitcnt lgkmcnt(0)
	v_add_f32_e32 v4, v2, v3
	v_lshlrev_b64 v[2:3], 6, v[18:19]
	v_lshl_add_u64 v[2:3], s[36:37], 0, v[2:3]
	v_lshl_add_u64 v[2:3], s[50:51], 2, v[2:3]
	s_lshl_b32 s70, s65, 2
	v_lshl_add_u64 v[2:3], v[2:3], 0, s[70:71]
	global_store_dword v[2:3], v4, off
